# combo_bjmix_noprio_maxtrim_backedge
# speedup vs baseline: 1.0154x; 1.0085x over previous
.LBB0_361:
	s_waitcnt lgkmcnt(14)
	v_mfma_f32_32x32x16_bf16 v[64:79], v[180:183], v[112:115], v[64:79]
	v_exp_f32_e32 v144, v144
	v_exp_f32_e32 v145, v145
	ds_read_b64_tr_b16 v[112:113], v0 offset:32768
	ds_read_b64_tr_b16 v[114:115], v0 offset:33280
	s_waitcnt lgkmcnt(14)
	v_mfma_f32_32x32x16_bf16 v[48:63], v[180:183], v[96:99], v[48:63]
	v_exp_f32_e32 v146, v146
	v_exp_f32_e32 v147, v147
	ds_read_b64_tr_b16 v[116:117], v0 offset:36864
	ds_read_b64_tr_b16 v[118:119], v0 offset:37376
	v_add_u32_e32 v211, s8, v224
	ds_read_b128 v[96:99], v211
	ds_read_b128 v[200:203], v211 offset:512
	s_waitcnt lgkmcnt(14)
	v_mfma_f32_32x32x16_bf16 v[64:79], v[172:175], v[10:13], v[64:79]
	v_exp_f32_e32 v148, v148
	v_exp_f32_e32 v149, v149
	ds_read_b64_tr_b16 v[120:121], v0 offset:33792
	ds_read_b64_tr_b16 v[122:123], v0 offset:34304
	ds_read_b128 v[204:207], v211 offset:2048
	ds_read_b128 v[196:199], v211 offset:2560
	v_mfma_f32_32x32x16_bf16 v[48:63], v[172:175], v[6:9], v[48:63]
	v_exp_f32_e32 v150, v150
	v_exp_f32_e32 v151, v151
	ds_read_b64_tr_b16 v[124:125], v0 offset:37888
	ds_read_b64_tr_b16 v[126:127], v0 offset:38400
	ds_read_b128 v[192:195], v211 offset:4096
	ds_read_b128 v[10:13], v211 offset:4608
	s_waitcnt lgkmcnt(14)
	v_mfma_f32_32x32x16_bf16 v[64:79], v[164:167], v[2:5], v[64:79]
	v_exp_f32_e32 v152, v152
	v_exp_f32_e32 v153, v153
	ds_read_b64_tr_b16 v[212:213], v0 offset:34816
	ds_read_b64_tr_b16 v[214:215], v0 offset:35328
	ds_read_b128 v[6:9], v211 offset:6144
	ds_read_b128 v[2:5], v211 offset:6656
	v_mfma_f32_32x32x16_bf16 v[48:63], v[164:167], v[108:111], v[48:63]
	v_exp_f32_e32 v154, v154
	v_exp_f32_e32 v155, v155
	ds_read_b64_tr_b16 v[108:109], v0 offset:38912
	ds_read_b64_tr_b16 v[110:111], v0 offset:39424
	v_mfma_f32_32x32x16_bf16 v[64:79], v[160:163], v[104:107], v[64:79]
	v_exp_f32_e32 v156, v156
	v_exp_f32_e32 v157, v157
	ds_read_b64_tr_b16 v[104:105], v0 offset:35840
	ds_read_b64_tr_b16 v[106:107], v0 offset:36352
	v_mfma_f32_32x32x16_bf16 v[48:63], v[160:163], v[100:103], v[48:63]
	v_exp_f32_e32 v158, v158
	v_exp_f32_e32 v159, v159
	ds_read_b64_tr_b16 v[100:101], v0 offset:39936
	ds_read_b64_tr_b16 v[102:103], v0 offset:40448
	s_waitcnt lgkmcnt(14)
	v_mfma_f32_32x32x16_bf16 v[32:47], v[180:183], v[112:115], v[32:47]
	v_exp_f32_e32 v128, v128
	v_exp_f32_e32 v129, v129
	v_mfma_f32_32x32x16_bf16 v[16:31], v[180:183], v[116:119], v[16:31]
	v_exp_f32_e32 v130, v130
	v_exp_f32_e32 v131, v131
	v_mfma_f32_32x32x16_bf16 v[32:47], v[172:175], v[120:123], v[32:47]
	v_exp_f32_e32 v132, v132
	v_exp_f32_e32 v133, v133
	s_waitcnt lgkmcnt(12)
	v_mfma_f32_32x32x16_bf16 v[16:31], v[172:175], v[124:127], v[16:31]
	v_exp_f32_e32 v134, v134
	v_exp_f32_e32 v135, v135
	s_waitcnt lgkmcnt(8)
	v_mfma_f32_32x32x16_bf16 v[32:47], v[164:167], v[212:215], v[32:47]
	v_exp_f32_e32 v136, v136
	v_exp_f32_e32 v137, v137
	s_waitcnt lgkmcnt(4)
	v_mfma_f32_32x32x16_bf16 v[16:31], v[164:167], v[108:111], v[16:31]
	v_exp_f32_e32 v138, v138
	v_exp_f32_e32 v139, v139
	s_waitcnt lgkmcnt(2)
	v_mfma_f32_32x32x16_bf16 v[32:47], v[160:163], v[104:107], v[32:47]
	v_exp_f32_e32 v140, v140
	v_exp_f32_e32 v141, v141
	s_waitcnt lgkmcnt(0)
	v_mfma_f32_32x32x16_bf16 v[16:31], v[160:163], v[100:103], v[16:31]
	v_exp_f32_e32 v142, v142
	v_exp_f32_e32 v143, v143
	s_andn2_b64 vcc, exec, s[2:3]
	v_add_u32_e32 v0, s66, v226
	s_add_i32 s2, s8, 0x2000
	s_cmpk_lg_i32 s8, 0x4000
	s_cselect_b32 s68, s2, 0
	s_waitcnt vmcnt(3) lgkmcnt(0)
	s_barrier
	s_cbranch_vccnz .LBB0_363
	s_waitcnt lgkmcnt(0)
	ds_read_b128 v[100:103], v0 offset:96
	ds_read_b128 v[104:107], v0 offset:64
	ds_read_b128 v[108:111], v0 offset:32
	ds_read_b128 v[112:115], v0
	s_waitcnt lgkmcnt(3)
	v_pk_mul_f32 v[76:77], v[76:77], v[100:101]
	s_waitcnt lgkmcnt(2)
	v_pk_mul_f32 v[72:73], v[72:73], v[104:105]
	s_waitcnt lgkmcnt(1)
	v_pk_mul_f32 v[68:69], v[68:69], v[108:109]
	v_pk_mul_f32 v[78:79], v[78:79], v[102:103]
	v_pk_mul_f32 v[74:75], v[74:75], v[106:107]
	v_pk_mul_f32 v[70:71], v[70:71], v[110:111]
	s_waitcnt lgkmcnt(0)
	v_pk_mul_f32 v[66:67], v[66:67], v[114:115]
	v_pk_mul_f32 v[64:65], v[64:65], v[112:113]
	v_pk_mul_f32 v[60:61], v[60:61], v[100:101]
	v_pk_mul_f32 v[56:57], v[56:57], v[104:105]
	v_pk_mul_f32 v[52:53], v[52:53], v[108:109]
	v_pk_mul_f32 v[62:63], v[62:63], v[102:103]
	v_pk_mul_f32 v[58:59], v[58:59], v[106:107]
	v_pk_mul_f32 v[54:55], v[54:55], v[110:111]
	v_pk_mul_f32 v[50:51], v[50:51], v[114:115]
	v_pk_mul_f32 v[48:49], v[48:49], v[112:113]
	v_pk_mul_f32 v[44:45], v[44:45], v[100:101]
	v_pk_mul_f32 v[40:41], v[40:41], v[104:105]
	v_pk_mul_f32 v[36:37], v[36:37], v[108:109]
	v_pk_mul_f32 v[46:47], v[46:47], v[102:103]
	v_pk_mul_f32 v[42:43], v[42:43], v[106:107]
	v_pk_mul_f32 v[38:39], v[38:39], v[110:111]
	v_pk_mul_f32 v[34:35], v[34:35], v[114:115]
	v_pk_mul_f32 v[32:33], v[32:33], v[112:113]
	v_pk_mul_f32 v[28:29], v[28:29], v[100:101]
	v_pk_mul_f32 v[24:25], v[24:25], v[104:105]
	v_pk_mul_f32 v[20:21], v[20:21], v[108:109]
	v_pk_mul_f32 v[30:31], v[30:31], v[102:103]
	v_pk_mul_f32 v[26:27], v[26:27], v[106:107]
	v_pk_mul_f32 v[22:23], v[22:23], v[110:111]
	v_pk_mul_f32 v[18:19], v[18:19], v[114:115]
	v_pk_mul_f32 v[16:17], v[16:17], v[112:113]
.LBB0_363:
	v_mfma_f32_32x32x16_bf16 v[112:127], v[96:99], v[188:191], v[80:95]
	v_add_f32_e32 v100, v144, v145
	v_add_f32_e32 v100, v146, v100
	v_add_f32_e32 v100, v147, v100
	s_lshl_b32 s2, s10, 1
	v_add_f32_e32 v100, v148, v100
	v_add_u32_e32 v230, s2, v225
	v_add_f32_e32 v96, v149, v100
	v_cvt_pk_bf16_f32 v180, v144, v145
	v_cvt_pk_bf16_f32 v181, v146, v147
	s_nop 0
	v_add_f32_e32 v96, v150, v96
	v_add_f32_e32 v96, v151, v96
	v_add_f32_e32 v96, v152, v96
	v_add_f32_e32 v144, v153, v96
	v_mfma_f32_32x32x16_bf16 v[96:111], v[200:203], v[188:191], v[80:95]
	v_cvt_pk_bf16_f32 v182, v148, v149
	v_cvt_pk_bf16_f32 v183, v150, v151
	v_mfma_f32_32x32x16_bf16 v[112:127], v[204:207], v[184:187], v[112:127]
	v_add_f32_e32 v144, v154, v144
	v_add_f32_e32 v144, v155, v144
	v_add_f32_e32 v144, v156, v144
	v_add_f32_e32 v144, v157, v144
	v_cvt_pk_bf16_f32 v172, v152, v153
	v_cvt_pk_bf16_f32 v173, v154, v155
	v_mfma_f32_32x32x16_bf16 v[96:111], v[196:199], v[184:187], v[96:111]
	v_add_f32_e32 v144, v158, v144
	v_add_f32_e32 v144, v159, v144
	v_add_f32_e32 v144, v128, v144
	v_add_f32_e32 v144, v129, v144
	v_cvt_pk_bf16_f32 v174, v156, v157
	v_cvt_pk_bf16_f32 v175, v158, v159
	v_mfma_f32_32x32x16_bf16 v[112:127], v[192:195], v[176:179], v[112:127]
	v_add_f32_e32 v144, v130, v144
	v_add_f32_e32 v144, v131, v144
	v_add_f32_e32 v144, v132, v144
	v_add_f32_e32 v144, v133, v144
	v_cvt_pk_bf16_f32 v164, v128, v129
	v_cvt_pk_bf16_f32 v165, v130, v131
	v_mfma_f32_32x32x16_bf16 v[96:111], v[10:13], v[176:179], v[96:111]
	v_add_f32_e32 v10, v134, v144
	v_add_f32_e32 v10, v135, v10
	v_add_f32_e32 v10, v136, v10
	v_add_f32_e32 v10, v137, v10
	v_cvt_pk_bf16_f32 v166, v132, v133
	v_cvt_pk_bf16_f32 v167, v134, v135
	v_mfma_f32_32x32x16_bf16 v[112:127], v[6:9], v[168:171], v[112:127]
	v_add_f32_e32 v6, v138, v10
	v_add_f32_e32 v6, v139, v6
	v_add_f32_e32 v6, v140, v6
	v_add_f32_e32 v6, v141, v6
	v_cvt_pk_bf16_f32 v160, v136, v137
	v_cvt_pk_bf16_f32 v161, v138, v139
	v_mfma_f32_32x32x16_bf16 v[96:111], v[2:5], v[168:171], v[96:111]
	v_add_f32_e32 v2, v142, v6
	v_add_f32_e32 v2, v143, v2
	v_add_f32_e32 v150, 0, v2
	v_cvt_pk_bf16_f32 v162, v140, v141
	v_cvt_pk_bf16_f32 v163, v142, v143
	ds_read_b64_tr_b16 v[144:145], v230 offset:24576
	ds_read_b64_tr_b16 v[146:147], v230 offset:25088
	ds_read_b64_tr_b16 v[140:141], v230 offset:28672
	ds_read_b64_tr_b16 v[142:143], v230 offset:29184
	ds_read_b64_tr_b16 v[136:137], v230 offset:25600
	ds_read_b64_tr_b16 v[138:139], v230 offset:26112
	ds_read_b64_tr_b16 v[132:133], v230 offset:29696
	ds_read_b64_tr_b16 v[134:135], v230 offset:30208
	ds_read_b64_tr_b16 v[128:129], v230 offset:26624
	ds_read_b64_tr_b16 v[130:131], v230 offset:27136
	ds_read_b64_tr_b16 v[10:11], v230 offset:30720
	ds_read_b64_tr_b16 v[12:13], v230 offset:31232
	ds_read_b64_tr_b16 v[6:7], v230 offset:27648
	ds_read_b64_tr_b16 v[8:9], v230 offset:28160
	ds_read_b64_tr_b16 v[2:3], v230 offset:31744
	ds_read_b64_tr_b16 v[4:5], v230 offset:32256
	s_mov_b64 s[2:3], 0xa0000
	v_lshl_add_u64 v[148:149], v[208:209], 0, s[2:3]
	s_add_i32 s2, s8, s84
	s_mov_b32 s3, m0
	s_mov_b32 m0, s2
	s_nop 0
	global_load_lds_dwordx4 v[148:149], off
	s_mov_b32 m0, s3
	s_mov_b64 s[2:3], 0x24860000
	v_lshl_add_u64 v[148:149], v[14:15], 0, s[2:3]
	s_lshl_b32 s2, s68, 1
	s_add_i32 s6, s2, s82
	s_mov_b32 s2, m0
	s_mov_b32 m0, s6
	s_nop 0
	global_load_lds_dwordx4 v[148:149], off
	s_mov_b32 m0, s2
	s_mov_b64 s[2:3], 0x24860080
	v_lshl_add_u64 v[14:15], v[14:15], 0, s[2:3]
	s_add_i32 s2, s6, 0x2000
	s_mov_b32 s3, m0
	s_mov_b32 m0, s2
	s_nop 0
	global_load_lds_dwordx4 v[14:15], off
	s_mov_b32 m0, s3
	v_max_f32_e32 v14, v112, v113
	v_max3_f32 v15, v114, v115, v97
	v_max3_f32 v14, v14, v96, v98
	v_max3_f32 v14, v14, v99, v116
	v_max3_f32 v15, v15, v118, v119
	v_max3_f32 v14, v14, v117, v100
	v_max3_f32 v15, v15, v102, v103
	v_max3_f32 v14, v14, v101, v120
	v_max3_f32 v15, v15, v122, v123
	v_max3_f32 v14, v14, v121, v104
	v_max3_f32 v15, v15, v106, v107
	v_max3_f32 v14, v14, v105, v124
	v_max3_f32 v15, v15, v126, v127
	v_max3_f32 v14, v14, v125, v108
	v_max3_f32 v15, v15, v110, v111
	v_max3_f32 v14, v14, v109, v15
	v_mov_b32_e32 v15, v14
	s_nop 1
	v_permlane32_swap_b32_e32 v14, v15
	v_max_f32_e32 v14, v14, v15
	v_cmp_lt_f32_e32 vcc, s67, v14
	s_cmp_lg_u64 vcc, 0
	v_add_f32_e32 v227, v210, v150
	s_cselect_b64 s[2:3], -1, 0
	s_cbranch_vccnz .LBB0_371
.LBB0_364:
	s_waitcnt lgkmcnt(14)
	v_mfma_f32_32x32x16_bf16 v[64:79], v[180:183], v[144:147], v[64:79]
	v_exp_f32_e32 v112, v112
	v_exp_f32_e32 v113, v113
	ds_read_b64_tr_b16 v[144:145], v230 offset:32768
	ds_read_b64_tr_b16 v[146:147], v230 offset:33280
	s_waitcnt lgkmcnt(14)
	v_mfma_f32_32x32x16_bf16 v[48:63], v[180:183], v[140:143], v[48:63]
	v_exp_f32_e32 v114, v114
	v_exp_f32_e32 v115, v115
	ds_read_b64_tr_b16 v[140:141], v230 offset:36864
	ds_read_b64_tr_b16 v[142:143], v230 offset:37376
	v_add_u32_e32 v14, s68, v224
	ds_read_b128 v[220:223], v14
	ds_read_b128 v[216:219], v14 offset:512
	s_waitcnt lgkmcnt(14)
	v_mfma_f32_32x32x16_bf16 v[64:79], v[172:175], v[136:139], v[64:79]
	v_exp_f32_e32 v116, v116
	v_exp_f32_e32 v117, v117
	ds_read_b64_tr_b16 v[136:137], v230 offset:33792
	ds_read_b64_tr_b16 v[138:139], v230 offset:34304
	ds_read_b128 v[212:215], v14 offset:2048
	ds_read_b128 v[208:211], v14 offset:2560
	v_mfma_f32_32x32x16_bf16 v[48:63], v[172:175], v[132:135], v[48:63]
	v_exp_f32_e32 v118, v118
	v_exp_f32_e32 v119, v119
	ds_read_b64_tr_b16 v[132:133], v230 offset:37888
	ds_read_b64_tr_b16 v[134:135], v230 offset:38400
	ds_read_b128 v[204:207], v14 offset:4096
	ds_read_b128 v[200:203], v14 offset:4608
	s_waitcnt lgkmcnt(14)
	v_mfma_f32_32x32x16_bf16 v[64:79], v[164:167], v[128:131], v[64:79]
	v_exp_f32_e32 v120, v120
	v_exp_f32_e32 v121, v121
	ds_read_b64_tr_b16 v[128:129], v230 offset:34816
	ds_read_b64_tr_b16 v[130:131], v230 offset:35328
	ds_read_b128 v[196:199], v14 offset:6144
	ds_read_b128 v[192:195], v14 offset:6656
	v_mfma_f32_32x32x16_bf16 v[48:63], v[164:167], v[10:13], v[48:63]
	v_exp_f32_e32 v122, v122
	v_exp_f32_e32 v123, v123
	ds_read_b64_tr_b16 v[10:11], v230 offset:38912
	ds_read_b64_tr_b16 v[12:13], v230 offset:39424
	v_mfma_f32_32x32x16_bf16 v[64:79], v[160:163], v[6:9], v[64:79]
	v_exp_f32_e32 v124, v124
	v_exp_f32_e32 v125, v125
	ds_read_b64_tr_b16 v[6:7], v230 offset:35840
	ds_read_b64_tr_b16 v[8:9], v230 offset:36352
	v_mfma_f32_32x32x16_bf16 v[48:63], v[160:163], v[2:5], v[48:63]
	v_exp_f32_e32 v126, v126
	v_exp_f32_e32 v127, v127
	ds_read_b64_tr_b16 v[2:3], v230 offset:39936
	ds_read_b64_tr_b16 v[4:5], v230 offset:40448
	s_waitcnt lgkmcnt(14)
	v_mfma_f32_32x32x16_bf16 v[32:47], v[180:183], v[144:147], v[32:47]
	v_exp_f32_e32 v96, v96
	v_exp_f32_e32 v97, v97
	v_mfma_f32_32x32x16_bf16 v[16:31], v[180:183], v[140:143], v[16:31]
	v_exp_f32_e32 v98, v98
	v_exp_f32_e32 v99, v99
	v_mfma_f32_32x32x16_bf16 v[32:47], v[172:175], v[136:139], v[32:47]
	v_exp_f32_e32 v100, v100
	v_exp_f32_e32 v101, v101
	s_waitcnt lgkmcnt(12)
	v_mfma_f32_32x32x16_bf16 v[16:31], v[172:175], v[132:135], v[16:31]
	v_exp_f32_e32 v102, v102
	v_exp_f32_e32 v103, v103
	s_waitcnt lgkmcnt(8)
	v_mfma_f32_32x32x16_bf16 v[32:47], v[164:167], v[128:131], v[32:47]
	v_exp_f32_e32 v104, v104
	v_exp_f32_e32 v105, v105
	s_waitcnt lgkmcnt(4)
	v_mfma_f32_32x32x16_bf16 v[16:31], v[164:167], v[10:13], v[16:31]
	v_exp_f32_e32 v106, v106
	v_exp_f32_e32 v107, v107
	s_waitcnt lgkmcnt(2)
	v_mfma_f32_32x32x16_bf16 v[32:47], v[160:163], v[6:9], v[32:47]
	v_exp_f32_e32 v108, v108
	v_exp_f32_e32 v109, v109
	s_waitcnt lgkmcnt(0)
	v_mfma_f32_32x32x16_bf16 v[16:31], v[160:163], v[2:5], v[16:31]
	v_exp_f32_e32 v110, v110
	v_exp_f32_e32 v111, v111
	s_andn2_b64 vcc, exec, s[2:3]
	s_add_i32 s2, s68, 0x2000
	s_cmpk_lg_i32 s68, 0x4000
	s_cselect_b32 s72, s2, 0
	s_add_i32 s2, s9, 2
	s_add_u32 s4, s4, 0x40000
	s_addc_u32 s5, s5, 0
	s_cmp_ge_u32 s2, s85
	s_waitcnt vmcnt(3) lgkmcnt(0)
	s_barrier
	s_cbranch_vccnz .LBB0_366
	s_waitcnt lgkmcnt(0)
	ds_read_b128 v[2:5], v0 offset:96
	ds_read_b128 v[6:9], v0 offset:64
	ds_read_b128 v[10:13], v0 offset:32
	ds_read_b128 v[128:131], v0
	s_waitcnt lgkmcnt(3)
	v_pk_mul_f32 v[76:77], v[76:77], v[2:3]
	s_waitcnt lgkmcnt(2)
	v_pk_mul_f32 v[72:73], v[72:73], v[6:7]
	s_waitcnt lgkmcnt(1)
	v_pk_mul_f32 v[68:69], v[68:69], v[10:11]
	v_pk_mul_f32 v[78:79], v[78:79], v[4:5]
	v_pk_mul_f32 v[74:75], v[74:75], v[8:9]
	v_pk_mul_f32 v[70:71], v[70:71], v[12:13]
	s_waitcnt lgkmcnt(0)
	v_pk_mul_f32 v[66:67], v[66:67], v[130:131]
	v_pk_mul_f32 v[64:65], v[64:65], v[128:129]
	v_pk_mul_f32 v[60:61], v[60:61], v[2:3]
	v_pk_mul_f32 v[56:57], v[56:57], v[6:7]
	v_pk_mul_f32 v[52:53], v[52:53], v[10:11]
	v_pk_mul_f32 v[62:63], v[62:63], v[4:5]
	v_pk_mul_f32 v[58:59], v[58:59], v[8:9]
	v_pk_mul_f32 v[54:55], v[54:55], v[12:13]
	v_pk_mul_f32 v[50:51], v[50:51], v[130:131]
	v_pk_mul_f32 v[48:49], v[48:49], v[128:129]
	v_pk_mul_f32 v[44:45], v[44:45], v[2:3]
	v_pk_mul_f32 v[40:41], v[40:41], v[6:7]
	v_pk_mul_f32 v[36:37], v[36:37], v[10:11]
	v_pk_mul_f32 v[46:47], v[46:47], v[4:5]
	v_pk_mul_f32 v[42:43], v[42:43], v[8:9]
	v_pk_mul_f32 v[38:39], v[38:39], v[12:13]
	v_pk_mul_f32 v[34:35], v[34:35], v[130:131]
	v_pk_mul_f32 v[32:33], v[32:33], v[128:129]
	v_pk_mul_f32 v[28:29], v[28:29], v[2:3]
	v_pk_mul_f32 v[24:25], v[24:25], v[6:7]
	v_pk_mul_f32 v[20:21], v[20:21], v[10:11]
	v_pk_mul_f32 v[30:31], v[30:31], v[4:5]
	v_pk_mul_f32 v[26:27], v[26:27], v[8:9]
	v_pk_mul_f32 v[22:23], v[22:23], v[12:13]
	v_pk_mul_f32 v[18:19], v[18:19], v[130:131]
	v_pk_mul_f32 v[16:17], v[16:17], v[128:129]
.LBB0_366:
	s_cbranch_scc1 .LBB0_377
	s_mov_b32 s9, s2
	s_mov_b32 s2, s8
	s_mov_b32 s10, s68
	s_mov_b32 s8, s72
	s_branch .LBB0_360

.LBB0_468:
	s_ashr_i32 s37, s36, 31
	s_lshl_b64 s[40:41], s[36:37], 19
	s_add_u32 s40, s82, s40
	s_addc_u32 s41, s83, s41
	s_and_b64 s[42:43], s[10:11], exec
	s_cselect_b32 s5, s41, s9
	s_cselect_b32 s7, s40, s8
	s_ashr_i32 s39, s38, 31
	s_lshl_b64 s[42:43], s[38:39], 19
	s_add_u32 s42, s12, s42
	s_addc_u32 s43, s13, s43
	s_and_b64 s[44:45], s[10:11], exec
	s_cselect_b32 s37, s43, s3
	s_cselect_b32 s39, s42, s2
	s_add_u32 s8, s8, 0x40080
	s_addc_u32 s9, s9, 0
	s_add_u32 s33, s2, 0x100
	s_addc_u32 s61, s3, 0
	s_mov_b32 s62, -2
	s_add_u32 s2, s8, 0xfffc0080
	s_addc_u32 s3, s9, -1
	s_add_i32 s63, 0, 0x10000
	s_cmp_eq_u32 s62, 12
	s_cselect_b32 s45, s5, s3
	s_cselect_b32 s44, s7, s2
	s_cselect_b32 s3, s37, s61
	s_cselect_b32 s2, s39, s33
	s_add_i32 s66, 0, 0x14000
	v_add_u32_e32 v70, s63, v211
	v_add_u32_e32 v142, s66, v211
	ds_read_b128 v[50:53], v70
	ds_read_b128 v[54:57], v70 offset:1024
	ds_read_b128 v[66:69], v70 offset:2048
	ds_read_b128 v[70:73], v70 offset:3072
	ds_read_b128 v[90:93], v142
	ds_read_b128 v[110:113], v142 offset:1024
	ds_read_b128 v[126:129], v142 offset:2048
	ds_read_b128 v[142:145], v142 offset:3072
	v_lshl_add_u64 v[214:215], s[8:9], 0, v[172:173]
	s_add_i32 m0, s50, 0xc000
	ds_read_b128 v[176:179], v213
	ds_read_b128 v[180:183], v213 offset:1024
	ds_read_b128 v[186:189], v213 offset:2048
	ds_read_b128 v[190:193], v213 offset:3072
	ds_read_b128 v[194:197], v213 offset:4096
	ds_read_b128 v[198:201], v213 offset:5120
	ds_read_b128 v[202:205], v213 offset:6144
	ds_read_b128 v[206:209], v213 offset:7168
	global_load_lds_dwordx4 v[214:215], off
	v_lshl_add_u64 v[214:215], s[8:9], 0, v[174:175]
	s_add_i32 m0, s50, 0xe000
	s_nop 0
	global_load_lds_dwordx4 v[214:215], off
	s_waitcnt vmcnt(8)
	s_waitcnt lgkmcnt(0)
	s_barrier
	s_waitcnt lgkmcnt(0)
	v_mfma_f32_16x16x32_bf16 v[158:161], v[50:53], v[176:179], 0
	v_mfma_f32_16x16x32_bf16 v[158:161], v[54:57], v[180:183], v[158:161]
	v_mfma_f32_16x16x32_bf16 v[150:153], v[90:93], v[176:179], 0
	v_mfma_f32_16x16x32_bf16 v[150:153], v[110:113], v[180:183], v[150:153]
	v_mfma_f32_16x16x32_bf16 v[154:157], v[66:69], v[176:179], 0
	v_mfma_f32_16x16x32_bf16 v[154:157], v[70:73], v[180:183], v[154:157]
	v_mfma_f32_16x16x32_bf16 v[146:149], v[126:129], v[176:179], 0
	v_mfma_f32_16x16x32_bf16 v[146:149], v[142:145], v[180:183], v[146:149]
	v_mfma_f32_16x16x32_bf16 v[138:141], v[50:53], v[186:189], 0
	v_mfma_f32_16x16x32_bf16 v[138:141], v[54:57], v[190:193], v[138:141]
	v_mfma_f32_16x16x32_bf16 v[130:133], v[90:93], v[186:189], 0
	v_mfma_f32_16x16x32_bf16 v[130:133], v[110:113], v[190:193], v[130:133]
	v_mfma_f32_16x16x32_bf16 v[134:137], v[66:69], v[186:189], 0
	v_mfma_f32_16x16x32_bf16 v[134:137], v[70:73], v[190:193], v[134:137]
	v_mfma_f32_16x16x32_bf16 v[122:125], v[126:129], v[186:189], 0
	v_mfma_f32_16x16x32_bf16 v[122:125], v[142:145], v[190:193], v[122:125]
	v_mfma_f32_16x16x32_bf16 v[118:121], v[50:53], v[194:197], 0
	v_mfma_f32_16x16x32_bf16 v[118:121], v[54:57], v[198:201], v[118:121]
	v_mfma_f32_16x16x32_bf16 v[106:109], v[90:93], v[194:197], 0
	v_mfma_f32_16x16x32_bf16 v[106:109], v[110:113], v[198:201], v[106:109]
	v_mfma_f32_16x16x32_bf16 v[114:117], v[66:69], v[194:197], 0
	v_mfma_f32_16x16x32_bf16 v[114:117], v[70:73], v[198:201], v[114:117]
	v_mfma_f32_16x16x32_bf16 v[102:105], v[126:129], v[194:197], 0
	v_mfma_f32_16x16x32_bf16 v[102:105], v[142:145], v[198:201], v[102:105]
	v_mfma_f32_16x16x32_bf16 v[98:101], v[50:53], v[202:205], 0
	v_mfma_f32_16x16x32_bf16 v[98:101], v[54:57], v[206:209], v[98:101]
	v_mfma_f32_16x16x32_bf16 v[86:89], v[90:93], v[202:205], 0
	v_mfma_f32_16x16x32_bf16 v[86:89], v[110:113], v[206:209], v[86:89]
	v_mfma_f32_16x16x32_bf16 v[94:97], v[66:69], v[202:205], 0
	v_mfma_f32_16x16x32_bf16 v[94:97], v[70:73], v[206:209], v[94:97]
	v_mfma_f32_16x16x32_bf16 v[82:85], v[126:129], v[202:205], 0
	v_mfma_f32_16x16x32_bf16 v[82:85], v[142:145], v[206:209], v[82:85]
	s_barrier
	s_add_i32 s63, s63, s49
	v_lshl_add_u64 v[214:215], s[2:3], 0, v[0:1]
	s_mov_b32 m0, s63
	ds_read_b128 v[176:179], v213 offset:16384
	ds_read_b128 v[180:183], v213 offset:17408
	ds_read_b128 v[186:189], v213 offset:18432
	ds_read_b128 v[190:193], v213 offset:19456
	ds_read_b128 v[194:197], v213 offset:20480
	ds_read_b128 v[198:201], v213 offset:21504
	ds_read_b128 v[202:205], v213 offset:22528
	ds_read_b128 v[206:209], v213 offset:23552
	global_load_lds_dwordx4 v[214:215], off
	s_add_i32 m0, s63, 0x2000
	s_add_u32 s64, s2, 0x40000
	v_lshl_add_u64 v[216:217], s[2:3], 0, v[166:167]
	s_addc_u32 s65, s3, 0
	s_add_i32 s63, s66, s49
	global_load_lds_dwordx4 v[216:217], off
	v_lshl_add_u64 v[218:219], s[64:65], 0, v[0:1]
	s_mov_b32 m0, s63
	v_lshl_add_u64 v[220:221], s[44:45], 0, v[164:165]
	global_load_lds_dwordx4 v[218:219], off
	v_lshl_add_u64 v[218:219], s[64:65], 0, v[166:167]
	s_add_i32 m0, s63, 0x2000
	s_nop 0
	global_load_lds_dwordx4 v[218:219], off
	v_lshl_add_u64 v[218:219], s[44:45], 0, v[162:163]
	s_mov_b32 m0, s50
	s_nop 0
	global_load_lds_dwordx4 v[218:219], off
	s_mov_b32 m0, s51
	s_nop 0
	global_load_lds_dwordx4 v[220:221], off
	s_waitcnt vmcnt(8)
	s_waitcnt lgkmcnt(0)
	s_barrier
	s_waitcnt lgkmcnt(0)
	v_mfma_f32_16x16x32_bf16 v[78:81], v[50:53], v[176:179], 0
	v_mfma_f32_16x16x32_bf16 v[78:81], v[54:57], v[180:183], v[78:81]
	v_mfma_f32_16x16x32_bf16 v[38:41], v[90:93], v[186:189], 0
	v_mfma_f32_16x16x32_bf16 v[38:41], v[110:113], v[190:193], v[38:41]
	v_mfma_f32_16x16x32_bf16 v[74:77], v[66:69], v[176:179], 0
	v_mfma_f32_16x16x32_bf16 v[74:77], v[70:73], v[180:183], v[74:77]
	v_mfma_f32_16x16x32_bf16 v[34:37], v[126:129], v[186:189], 0
	v_mfma_f32_16x16x32_bf16 v[34:37], v[142:145], v[190:193], v[34:37]
	v_mfma_f32_16x16x32_bf16 v[46:49], v[50:53], v[186:189], 0
	v_mfma_f32_16x16x32_bf16 v[46:49], v[54:57], v[190:193], v[46:49]
	v_mfma_f32_16x16x32_bf16 v[22:25], v[90:93], v[194:197], 0
	v_mfma_f32_16x16x32_bf16 v[22:25], v[110:113], v[198:201], v[22:25]
	v_mfma_f32_16x16x32_bf16 v[42:45], v[66:69], v[186:189], 0
	v_mfma_f32_16x16x32_bf16 v[42:45], v[70:73], v[190:193], v[42:45]
	v_mfma_f32_16x16x32_bf16 v[18:21], v[126:129], v[194:197], 0
	v_mfma_f32_16x16x32_bf16 v[18:21], v[142:145], v[198:201], v[18:21]
	v_mfma_f32_16x16x32_bf16 v[30:33], v[50:53], v[194:197], 0
	v_mfma_f32_16x16x32_bf16 v[30:33], v[54:57], v[198:201], v[30:33]
	v_mfma_f32_16x16x32_bf16 v[6:9], v[90:93], v[202:205], 0
	v_mfma_f32_16x16x32_bf16 v[6:9], v[110:113], v[206:209], v[6:9]
	v_mfma_f32_16x16x32_bf16 v[26:29], v[66:69], v[194:197], 0
	v_mfma_f32_16x16x32_bf16 v[26:29], v[70:73], v[198:201], v[26:29]
	v_mfma_f32_16x16x32_bf16 v[2:5], v[126:129], v[202:205], 0
	v_mfma_f32_16x16x32_bf16 v[2:5], v[142:145], v[206:209], v[2:5]
	v_mfma_f32_16x16x32_bf16 v[14:17], v[50:53], v[202:205], 0
	v_mfma_f32_16x16x32_bf16 v[14:17], v[54:57], v[206:209], v[14:17]
	v_mfma_f32_16x16x32_bf16 v[50:53], v[90:93], v[176:179], 0
	v_mfma_f32_16x16x32_bf16 v[50:53], v[110:113], v[180:183], v[50:53]
	v_mfma_f32_16x16x32_bf16 v[10:13], v[66:69], v[202:205], 0
	v_mfma_f32_16x16x32_bf16 v[10:13], v[70:73], v[206:209], v[10:13]
	v_mfma_f32_16x16x32_bf16 v[54:57], v[126:129], v[176:179], 0
	v_mfma_f32_16x16x32_bf16 v[54:57], v[142:145], v[180:183], v[54:57]
	s_barrier
	s_add_i32 s63, 0, 0x18000
	s_add_i32 s64, 0, 0x1c000
	v_add_u32_e32 v70, s63, v211
	v_add_u32_e32 v142, s64, v211
	ds_read_b128 v[58:61], v70
	ds_read_b128 v[62:65], v70 offset:1024
	ds_read_b128 v[66:69], v70 offset:2048
	ds_read_b128 v[70:73], v70 offset:3072
	ds_read_b128 v[90:93], v142
	ds_read_b128 v[110:113], v142 offset:1024
	ds_read_b128 v[126:129], v142 offset:2048
	ds_read_b128 v[142:145], v142 offset:3072
	s_add_u32 s44, s44, 0x40000
	s_addc_u32 s45, s45, 0
	s_mov_b32 m0, s52
	v_lshl_add_u64 v[222:223], s[44:45], 0, v[162:163]
	ds_read_b128 v[176:179], v213 offset:32768
	ds_read_b128 v[180:183], v213 offset:33792
	ds_read_b128 v[186:189], v213 offset:34816
	ds_read_b128 v[190:193], v213 offset:35840
	ds_read_b128 v[194:197], v213 offset:36864
	ds_read_b128 v[198:201], v213 offset:37888
	ds_read_b128 v[202:205], v213 offset:38912
	ds_read_b128 v[206:209], v213 offset:39936
	global_load_lds_dwordx4 v[222:223], off
	v_lshl_add_u64 v[222:223], s[44:45], 0, v[164:165]
	s_mov_b32 m0, s53
	s_nop 0
	global_load_lds_dwordx4 v[222:223], off
	s_waitcnt vmcnt(8)
	s_waitcnt lgkmcnt(0)
	s_barrier
	s_waitcnt lgkmcnt(0)
	v_mfma_f32_16x16x32_bf16 v[158:161], v[58:61], v[176:179], v[158:161]
	v_mfma_f32_16x16x32_bf16 v[158:161], v[62:65], v[180:183], v[158:161]
	v_mfma_f32_16x16x32_bf16 v[150:153], v[90:93], v[176:179], v[150:153]
	v_mfma_f32_16x16x32_bf16 v[150:153], v[110:113], v[180:183], v[150:153]
	v_mfma_f32_16x16x32_bf16 v[154:157], v[66:69], v[176:179], v[154:157]
	v_mfma_f32_16x16x32_bf16 v[154:157], v[70:73], v[180:183], v[154:157]
	v_mfma_f32_16x16x32_bf16 v[146:149], v[126:129], v[176:179], v[146:149]
	v_mfma_f32_16x16x32_bf16 v[146:149], v[142:145], v[180:183], v[146:149]
	v_mfma_f32_16x16x32_bf16 v[138:141], v[58:61], v[186:189], v[138:141]
	v_mfma_f32_16x16x32_bf16 v[138:141], v[62:65], v[190:193], v[138:141]
	v_mfma_f32_16x16x32_bf16 v[130:133], v[90:93], v[186:189], v[130:133]
	v_mfma_f32_16x16x32_bf16 v[130:133], v[110:113], v[190:193], v[130:133]
	v_mfma_f32_16x16x32_bf16 v[134:137], v[66:69], v[186:189], v[134:137]
	v_mfma_f32_16x16x32_bf16 v[134:137], v[70:73], v[190:193], v[134:137]
	v_mfma_f32_16x16x32_bf16 v[122:125], v[126:129], v[186:189], v[122:125]
	v_mfma_f32_16x16x32_bf16 v[122:125], v[142:145], v[190:193], v[122:125]
	v_mfma_f32_16x16x32_bf16 v[118:121], v[58:61], v[194:197], v[118:121]
	v_mfma_f32_16x16x32_bf16 v[118:121], v[62:65], v[198:201], v[118:121]
	v_mfma_f32_16x16x32_bf16 v[106:109], v[90:93], v[194:197], v[106:109]
	v_mfma_f32_16x16x32_bf16 v[106:109], v[110:113], v[198:201], v[106:109]
	v_mfma_f32_16x16x32_bf16 v[114:117], v[66:69], v[194:197], v[114:117]
	v_mfma_f32_16x16x32_bf16 v[114:117], v[70:73], v[198:201], v[114:117]
	v_mfma_f32_16x16x32_bf16 v[102:105], v[126:129], v[194:197], v[102:105]
	v_mfma_f32_16x16x32_bf16 v[102:105], v[142:145], v[198:201], v[102:105]
	v_mfma_f32_16x16x32_bf16 v[98:101], v[58:61], v[202:205], v[98:101]
	v_mfma_f32_16x16x32_bf16 v[98:101], v[62:65], v[206:209], v[98:101]
	v_mfma_f32_16x16x32_bf16 v[86:89], v[90:93], v[202:205], v[86:89]
	v_mfma_f32_16x16x32_bf16 v[86:89], v[110:113], v[206:209], v[86:89]
	v_mfma_f32_16x16x32_bf16 v[94:97], v[66:69], v[202:205], v[94:97]
	v_mfma_f32_16x16x32_bf16 v[94:97], v[70:73], v[206:209], v[94:97]
	v_mfma_f32_16x16x32_bf16 v[82:85], v[126:129], v[202:205], v[82:85]
	v_mfma_f32_16x16x32_bf16 v[82:85], v[142:145], v[206:209], v[82:85]
	s_barrier
	s_add_i32 s44, s63, s49
	v_lshl_add_u64 v[214:215], v[214:215], 0, s[74:75]
	s_mov_b32 m0, s44
	ds_read_b128 v[176:179], v213 offset:49152
	ds_read_b128 v[180:183], v213 offset:50176
	ds_read_b128 v[186:189], v213 offset:51200
	ds_read_b128 v[190:193], v213 offset:52224
	ds_read_b128 v[194:197], v213 offset:53248
	ds_read_b128 v[198:201], v213 offset:54272
	ds_read_b128 v[202:205], v213 offset:55296
	ds_read_b128 v[206:209], v213 offset:56320
	global_load_lds_dwordx4 v[214:215], off
	s_add_i32 m0, s44, 0x2000
	s_add_u32 s2, s2, 0x40080
	v_lshl_add_u64 v[214:215], v[216:217], 0, s[74:75]
	s_addc_u32 s3, s3, 0
	s_add_i32 s44, s64, s49
	global_load_lds_dwordx4 v[214:215], off
	v_lshl_add_u64 v[214:215], s[2:3], 0, v[0:1]
	s_mov_b32 m0, s44
	s_nop 0
	global_load_lds_dwordx4 v[214:215], off
	v_lshl_add_u64 v[214:215], s[2:3], 0, v[166:167]
	s_add_i32 m0, s44, 0x2000
	s_nop 0
	global_load_lds_dwordx4 v[214:215], off
	v_lshl_add_u64 v[214:215], v[218:219], 0, s[74:75]
	s_mov_b32 m0, s55
	s_nop 0
	global_load_lds_dwordx4 v[214:215], off
	v_lshl_add_u64 v[214:215], v[220:221], 0, s[74:75]
	s_mov_b32 m0, s56
	s_nop 0
	global_load_lds_dwordx4 v[214:215], off
	s_waitcnt vmcnt(8)
	s_waitcnt lgkmcnt(0)
	s_barrier
	s_waitcnt lgkmcnt(0)
	v_mfma_f32_16x16x32_bf16 v[78:81], v[58:61], v[176:179], v[78:81]
	v_mfma_f32_16x16x32_bf16 v[74:77], v[66:69], v[176:179], v[74:77]
	v_mfma_f32_16x16x32_bf16 v[46:49], v[58:61], v[186:189], v[46:49]
	v_mfma_f32_16x16x32_bf16 v[42:45], v[66:69], v[186:189], v[42:45]
	v_mfma_f32_16x16x32_bf16 v[30:33], v[58:61], v[194:197], v[30:33]
	v_mfma_f32_16x16x32_bf16 v[26:29], v[66:69], v[194:197], v[26:29]
	v_mfma_f32_16x16x32_bf16 v[14:17], v[58:61], v[202:205], v[14:17]
	v_mfma_f32_16x16x32_bf16 v[10:13], v[66:69], v[202:205], v[10:13]
	v_mfma_f32_16x16x32_bf16 v[78:81], v[62:65], v[180:183], v[78:81]
	v_mfma_f32_16x16x32_bf16 v[74:77], v[70:73], v[180:183], v[74:77]
	v_mfma_f32_16x16x32_bf16 v[46:49], v[62:65], v[190:193], v[46:49]
	v_mfma_f32_16x16x32_bf16 v[42:45], v[70:73], v[190:193], v[42:45]
	v_mfma_f32_16x16x32_bf16 v[30:33], v[62:65], v[198:201], v[30:33]
	v_mfma_f32_16x16x32_bf16 v[26:29], v[70:73], v[198:201], v[26:29]
	v_mfma_f32_16x16x32_bf16 v[14:17], v[62:65], v[206:209], v[14:17]
	v_mfma_f32_16x16x32_bf16 v[10:13], v[70:73], v[206:209], v[10:13]
	v_mfma_f32_16x16x32_bf16 v[50:53], v[90:93], v[176:179], v[50:53]
	v_mfma_f32_16x16x32_bf16 v[62:65], v[110:113], v[180:183], v[50:53]
	v_mfma_f32_16x16x32_bf16 v[50:53], v[126:129], v[176:179], v[54:57]
	v_mfma_f32_16x16x32_bf16 v[38:41], v[90:93], v[186:189], v[38:41]
	v_mfma_f32_16x16x32_bf16 v[34:37], v[126:129], v[186:189], v[34:37]
	v_mfma_f32_16x16x32_bf16 v[22:25], v[90:93], v[194:197], v[22:25]
	v_mfma_f32_16x16x32_bf16 v[18:21], v[126:129], v[194:197], v[18:21]
	v_mfma_f32_16x16x32_bf16 v[6:9], v[90:93], v[202:205], v[6:9]
	v_mfma_f32_16x16x32_bf16 v[2:5], v[126:129], v[202:205], v[2:5]
	v_mfma_f32_16x16x32_bf16 v[58:61], v[142:145], v[180:183], v[50:53]
	v_mfma_f32_16x16x32_bf16 v[38:41], v[110:113], v[190:193], v[38:41]
	v_mfma_f32_16x16x32_bf16 v[34:37], v[142:145], v[190:193], v[34:37]
	v_mfma_f32_16x16x32_bf16 v[22:25], v[110:113], v[198:201], v[22:25]
	v_mfma_f32_16x16x32_bf16 v[18:21], v[142:145], v[198:201], v[18:21]
	v_mfma_f32_16x16x32_bf16 v[6:9], v[110:113], v[206:209], v[6:9]
	v_mfma_f32_16x16x32_bf16 v[2:5], v[142:145], v[206:209], v[2:5]
	s_barrier
	s_add_i32 s62, s62, 2
	s_add_u32 s8, s8, 0x100
	s_addc_u32 s9, s9, 0
	s_add_u32 s33, s33, 0x100
	s_addc_u32 s61, s61, 0
	s_cmp_gt_u32 s62, 13
.LBB0_469:
	s_add_u32 s2, s8, 0xfffc0080
	s_addc_u32 s3, s9, -1
	s_add_i32 s63, 0, 0x10000
	s_cmp_eq_u32 s62, 12
	s_cselect_b32 s45, s5, s3
	s_cselect_b32 s44, s7, s2
	s_cselect_b32 s3, s37, s61
	s_cselect_b32 s2, s39, s33
	s_add_i32 s66, 0, 0x14000
	v_add_u32_e32 v70, s63, v211
	v_add_u32_e32 v142, s66, v211
	ds_read_b128 v[50:53], v70
	ds_read_b128 v[54:57], v70 offset:1024
	ds_read_b128 v[66:69], v70 offset:2048
	ds_read_b128 v[70:73], v70 offset:3072
	ds_read_b128 v[90:93], v142
	ds_read_b128 v[110:113], v142 offset:1024
	ds_read_b128 v[126:129], v142 offset:2048
	ds_read_b128 v[142:145], v142 offset:3072
	v_lshl_add_u64 v[214:215], s[8:9], 0, v[172:173]
	s_add_i32 m0, s50, 0xc000
	ds_read_b128 v[176:179], v213
	ds_read_b128 v[180:183], v213 offset:1024
	ds_read_b128 v[186:189], v213 offset:2048
	ds_read_b128 v[190:193], v213 offset:3072
	ds_read_b128 v[194:197], v213 offset:4096
	ds_read_b128 v[198:201], v213 offset:5120
	ds_read_b128 v[202:205], v213 offset:6144
	ds_read_b128 v[206:209], v213 offset:7168
	global_load_lds_dwordx4 v[214:215], off
	v_lshl_add_u64 v[214:215], s[8:9], 0, v[174:175]
	s_add_i32 m0, s50, 0xe000
	s_nop 0
	global_load_lds_dwordx4 v[214:215], off
	s_waitcnt vmcnt(8)
	s_waitcnt lgkmcnt(0)
	s_barrier
	s_waitcnt lgkmcnt(0)
	v_mfma_f32_16x16x32_bf16 v[158:161], v[50:53], v[176:179], v[158:161]
	v_mfma_f32_16x16x32_bf16 v[158:161], v[54:57], v[180:183], v[158:161]
	v_mfma_f32_16x16x32_bf16 v[150:153], v[90:93], v[176:179], v[150:153]
	v_mfma_f32_16x16x32_bf16 v[150:153], v[110:113], v[180:183], v[150:153]
	v_mfma_f32_16x16x32_bf16 v[154:157], v[66:69], v[176:179], v[154:157]
	v_mfma_f32_16x16x32_bf16 v[154:157], v[70:73], v[180:183], v[154:157]
	v_mfma_f32_16x16x32_bf16 v[146:149], v[126:129], v[176:179], v[146:149]
	v_mfma_f32_16x16x32_bf16 v[146:149], v[142:145], v[180:183], v[146:149]
	v_mfma_f32_16x16x32_bf16 v[138:141], v[50:53], v[186:189], v[138:141]
	v_mfma_f32_16x16x32_bf16 v[138:141], v[54:57], v[190:193], v[138:141]
	v_mfma_f32_16x16x32_bf16 v[130:133], v[90:93], v[186:189], v[130:133]
	v_mfma_f32_16x16x32_bf16 v[130:133], v[110:113], v[190:193], v[130:133]
	v_mfma_f32_16x16x32_bf16 v[134:137], v[66:69], v[186:189], v[134:137]
	v_mfma_f32_16x16x32_bf16 v[134:137], v[70:73], v[190:193], v[134:137]
	v_mfma_f32_16x16x32_bf16 v[122:125], v[126:129], v[186:189], v[122:125]
	v_mfma_f32_16x16x32_bf16 v[122:125], v[142:145], v[190:193], v[122:125]
	v_mfma_f32_16x16x32_bf16 v[118:121], v[50:53], v[194:197], v[118:121]
	v_mfma_f32_16x16x32_bf16 v[118:121], v[54:57], v[198:201], v[118:121]
	v_mfma_f32_16x16x32_bf16 v[106:109], v[90:93], v[194:197], v[106:109]
	v_mfma_f32_16x16x32_bf16 v[106:109], v[110:113], v[198:201], v[106:109]
	v_mfma_f32_16x16x32_bf16 v[114:117], v[66:69], v[194:197], v[114:117]
	v_mfma_f32_16x16x32_bf16 v[114:117], v[70:73], v[198:201], v[114:117]
	v_mfma_f32_16x16x32_bf16 v[102:105], v[126:129], v[194:197], v[102:105]
	v_mfma_f32_16x16x32_bf16 v[102:105], v[142:145], v[198:201], v[102:105]
	v_mfma_f32_16x16x32_bf16 v[98:101], v[50:53], v[202:205], v[98:101]
	v_mfma_f32_16x16x32_bf16 v[98:101], v[54:57], v[206:209], v[98:101]
	v_mfma_f32_16x16x32_bf16 v[86:89], v[90:93], v[202:205], v[86:89]
	v_mfma_f32_16x16x32_bf16 v[86:89], v[110:113], v[206:209], v[86:89]
	v_mfma_f32_16x16x32_bf16 v[94:97], v[66:69], v[202:205], v[94:97]
	v_mfma_f32_16x16x32_bf16 v[94:97], v[70:73], v[206:209], v[94:97]
	v_mfma_f32_16x16x32_bf16 v[82:85], v[126:129], v[202:205], v[82:85]
	v_mfma_f32_16x16x32_bf16 v[82:85], v[142:145], v[206:209], v[82:85]
	s_barrier
	s_add_i32 s63, s63, s49
	v_lshl_add_u64 v[214:215], s[2:3], 0, v[0:1]
	s_mov_b32 m0, s63
	ds_read_b128 v[176:179], v213 offset:16384
	ds_read_b128 v[180:183], v213 offset:17408
	ds_read_b128 v[186:189], v213 offset:18432
	ds_read_b128 v[190:193], v213 offset:19456
	ds_read_b128 v[194:197], v213 offset:20480
	ds_read_b128 v[198:201], v213 offset:21504
	ds_read_b128 v[202:205], v213 offset:22528
	ds_read_b128 v[206:209], v213 offset:23552
	global_load_lds_dwordx4 v[214:215], off
	s_add_i32 m0, s63, 0x2000
	s_add_u32 s64, s2, 0x40000
	v_lshl_add_u64 v[216:217], s[2:3], 0, v[166:167]
	s_addc_u32 s65, s3, 0
	s_add_i32 s63, s66, s49
	global_load_lds_dwordx4 v[216:217], off
	v_lshl_add_u64 v[218:219], s[64:65], 0, v[0:1]
	s_mov_b32 m0, s63
	v_lshl_add_u64 v[220:221], s[44:45], 0, v[164:165]
	global_load_lds_dwordx4 v[218:219], off
	v_lshl_add_u64 v[218:219], s[64:65], 0, v[166:167]
	s_add_i32 m0, s63, 0x2000
	s_nop 0
	global_load_lds_dwordx4 v[218:219], off
	v_lshl_add_u64 v[218:219], s[44:45], 0, v[162:163]
	s_mov_b32 m0, s50
	s_nop 0
	global_load_lds_dwordx4 v[218:219], off
	s_mov_b32 m0, s51
	s_nop 0
	global_load_lds_dwordx4 v[220:221], off
	s_waitcnt vmcnt(8)
	s_waitcnt lgkmcnt(0)
	s_barrier
	s_waitcnt lgkmcnt(0)
	v_mfma_f32_16x16x32_bf16 v[78:81], v[50:53], v[176:179], v[78:81]
	v_mfma_f32_16x16x32_bf16 v[78:81], v[54:57], v[180:183], v[78:81]
	v_mfma_f32_16x16x32_bf16 v[38:41], v[90:93], v[186:189], v[38:41]
	v_mfma_f32_16x16x32_bf16 v[38:41], v[110:113], v[190:193], v[38:41]
	v_mfma_f32_16x16x32_bf16 v[74:77], v[66:69], v[176:179], v[74:77]
	v_mfma_f32_16x16x32_bf16 v[74:77], v[70:73], v[180:183], v[74:77]
	v_mfma_f32_16x16x32_bf16 v[34:37], v[126:129], v[186:189], v[34:37]
	v_mfma_f32_16x16x32_bf16 v[34:37], v[142:145], v[190:193], v[34:37]
	v_mfma_f32_16x16x32_bf16 v[46:49], v[50:53], v[186:189], v[46:49]
	v_mfma_f32_16x16x32_bf16 v[46:49], v[54:57], v[190:193], v[46:49]
	v_mfma_f32_16x16x32_bf16 v[22:25], v[90:93], v[194:197], v[22:25]
	v_mfma_f32_16x16x32_bf16 v[22:25], v[110:113], v[198:201], v[22:25]
	v_mfma_f32_16x16x32_bf16 v[42:45], v[66:69], v[186:189], v[42:45]
	v_mfma_f32_16x16x32_bf16 v[42:45], v[70:73], v[190:193], v[42:45]
	v_mfma_f32_16x16x32_bf16 v[18:21], v[126:129], v[194:197], v[18:21]
	v_mfma_f32_16x16x32_bf16 v[18:21], v[142:145], v[198:201], v[18:21]
	v_mfma_f32_16x16x32_bf16 v[30:33], v[50:53], v[194:197], v[30:33]
	v_mfma_f32_16x16x32_bf16 v[30:33], v[54:57], v[198:201], v[30:33]
	v_mfma_f32_16x16x32_bf16 v[6:9], v[90:93], v[202:205], v[6:9]
	v_mfma_f32_16x16x32_bf16 v[6:9], v[110:113], v[206:209], v[6:9]
	v_mfma_f32_16x16x32_bf16 v[26:29], v[66:69], v[194:197], v[26:29]
	v_mfma_f32_16x16x32_bf16 v[26:29], v[70:73], v[198:201], v[26:29]
	v_mfma_f32_16x16x32_bf16 v[2:5], v[126:129], v[202:205], v[2:5]
	v_mfma_f32_16x16x32_bf16 v[2:5], v[142:145], v[206:209], v[2:5]
	v_mfma_f32_16x16x32_bf16 v[14:17], v[50:53], v[202:205], v[14:17]
	v_mfma_f32_16x16x32_bf16 v[14:17], v[54:57], v[206:209], v[14:17]
	v_mfma_f32_16x16x32_bf16 v[50:53], v[90:93], v[176:179], v[62:65]
	v_mfma_f32_16x16x32_bf16 v[50:53], v[110:113], v[180:183], v[50:53]
	v_mfma_f32_16x16x32_bf16 v[10:13], v[66:69], v[202:205], v[10:13]
	v_mfma_f32_16x16x32_bf16 v[10:13], v[70:73], v[206:209], v[10:13]
	v_mfma_f32_16x16x32_bf16 v[54:57], v[126:129], v[176:179], v[58:61]
	v_mfma_f32_16x16x32_bf16 v[54:57], v[142:145], v[180:183], v[54:57]
	s_barrier
	s_add_i32 s63, 0, 0x18000
	s_add_i32 s64, 0, 0x1c000
	v_add_u32_e32 v70, s63, v211
	v_add_u32_e32 v142, s64, v211
	ds_read_b128 v[58:61], v70
	ds_read_b128 v[62:65], v70 offset:1024
	ds_read_b128 v[66:69], v70 offset:2048
	ds_read_b128 v[70:73], v70 offset:3072
	ds_read_b128 v[90:93], v142
	ds_read_b128 v[110:113], v142 offset:1024
	ds_read_b128 v[126:129], v142 offset:2048
	ds_read_b128 v[142:145], v142 offset:3072
	s_add_u32 s44, s44, 0x40000
	s_addc_u32 s45, s45, 0
	s_mov_b32 m0, s52
	v_lshl_add_u64 v[222:223], s[44:45], 0, v[162:163]
	ds_read_b128 v[176:179], v213 offset:32768
	ds_read_b128 v[180:183], v213 offset:33792
	ds_read_b128 v[186:189], v213 offset:34816
	ds_read_b128 v[190:193], v213 offset:35840
	ds_read_b128 v[194:197], v213 offset:36864
	ds_read_b128 v[198:201], v213 offset:37888
	ds_read_b128 v[202:205], v213 offset:38912
	ds_read_b128 v[206:209], v213 offset:39936
	global_load_lds_dwordx4 v[222:223], off
	v_lshl_add_u64 v[222:223], s[44:45], 0, v[164:165]
	s_mov_b32 m0, s53
	s_nop 0
	global_load_lds_dwordx4 v[222:223], off
	s_waitcnt vmcnt(8)
	s_waitcnt lgkmcnt(0)
	s_barrier
	s_waitcnt lgkmcnt(0)
	v_mfma_f32_16x16x32_bf16 v[158:161], v[58:61], v[176:179], v[158:161]
	v_mfma_f32_16x16x32_bf16 v[158:161], v[62:65], v[180:183], v[158:161]
	v_mfma_f32_16x16x32_bf16 v[150:153], v[90:93], v[176:179], v[150:153]
	v_mfma_f32_16x16x32_bf16 v[150:153], v[110:113], v[180:183], v[150:153]
	v_mfma_f32_16x16x32_bf16 v[154:157], v[66:69], v[176:179], v[154:157]
	v_mfma_f32_16x16x32_bf16 v[154:157], v[70:73], v[180:183], v[154:157]
	v_mfma_f32_16x16x32_bf16 v[146:149], v[126:129], v[176:179], v[146:149]
	v_mfma_f32_16x16x32_bf16 v[146:149], v[142:145], v[180:183], v[146:149]
	v_mfma_f32_16x16x32_bf16 v[138:141], v[58:61], v[186:189], v[138:141]
	v_mfma_f32_16x16x32_bf16 v[138:141], v[62:65], v[190:193], v[138:141]
	v_mfma_f32_16x16x32_bf16 v[130:133], v[90:93], v[186:189], v[130:133]
	v_mfma_f32_16x16x32_bf16 v[130:133], v[110:113], v[190:193], v[130:133]
	v_mfma_f32_16x16x32_bf16 v[134:137], v[66:69], v[186:189], v[134:137]
	v_mfma_f32_16x16x32_bf16 v[134:137], v[70:73], v[190:193], v[134:137]
	v_mfma_f32_16x16x32_bf16 v[122:125], v[126:129], v[186:189], v[122:125]
	v_mfma_f32_16x16x32_bf16 v[122:125], v[142:145], v[190:193], v[122:125]
	v_mfma_f32_16x16x32_bf16 v[118:121], v[58:61], v[194:197], v[118:121]
	v_mfma_f32_16x16x32_bf16 v[118:121], v[62:65], v[198:201], v[118:121]
	v_mfma_f32_16x16x32_bf16 v[106:109], v[90:93], v[194:197], v[106:109]
	v_mfma_f32_16x16x32_bf16 v[106:109], v[110:113], v[198:201], v[106:109]
	v_mfma_f32_16x16x32_bf16 v[114:117], v[66:69], v[194:197], v[114:117]
	v_mfma_f32_16x16x32_bf16 v[114:117], v[70:73], v[198:201], v[114:117]
	v_mfma_f32_16x16x32_bf16 v[102:105], v[126:129], v[194:197], v[102:105]
	v_mfma_f32_16x16x32_bf16 v[102:105], v[142:145], v[198:201], v[102:105]
	v_mfma_f32_16x16x32_bf16 v[98:101], v[58:61], v[202:205], v[98:101]
	v_mfma_f32_16x16x32_bf16 v[98:101], v[62:65], v[206:209], v[98:101]
	v_mfma_f32_16x16x32_bf16 v[86:89], v[90:93], v[202:205], v[86:89]
	v_mfma_f32_16x16x32_bf16 v[86:89], v[110:113], v[206:209], v[86:89]
	v_mfma_f32_16x16x32_bf16 v[94:97], v[66:69], v[202:205], v[94:97]
	v_mfma_f32_16x16x32_bf16 v[94:97], v[70:73], v[206:209], v[94:97]
	v_mfma_f32_16x16x32_bf16 v[82:85], v[126:129], v[202:205], v[82:85]
	v_mfma_f32_16x16x32_bf16 v[82:85], v[142:145], v[206:209], v[82:85]
	s_barrier
	s_add_i32 s44, s63, s49
	v_lshl_add_u64 v[214:215], v[214:215], 0, s[74:75]
	s_mov_b32 m0, s44
	ds_read_b128 v[176:179], v213 offset:49152
	ds_read_b128 v[180:183], v213 offset:50176
	ds_read_b128 v[186:189], v213 offset:51200
	ds_read_b128 v[190:193], v213 offset:52224
	ds_read_b128 v[194:197], v213 offset:53248
	ds_read_b128 v[198:201], v213 offset:54272
	ds_read_b128 v[202:205], v213 offset:55296
	ds_read_b128 v[206:209], v213 offset:56320
	global_load_lds_dwordx4 v[214:215], off
	s_add_i32 m0, s44, 0x2000
	s_add_u32 s2, s2, 0x40080
	v_lshl_add_u64 v[214:215], v[216:217], 0, s[74:75]
	s_addc_u32 s3, s3, 0
	s_add_i32 s44, s64, s49
	global_load_lds_dwordx4 v[214:215], off
	v_lshl_add_u64 v[214:215], s[2:3], 0, v[0:1]
	s_mov_b32 m0, s44
	s_nop 0
	global_load_lds_dwordx4 v[214:215], off
	v_lshl_add_u64 v[214:215], s[2:3], 0, v[166:167]
	s_add_i32 m0, s44, 0x2000
	s_nop 0
	global_load_lds_dwordx4 v[214:215], off
	v_lshl_add_u64 v[214:215], v[218:219], 0, s[74:75]
	s_mov_b32 m0, s55
	s_nop 0
	global_load_lds_dwordx4 v[214:215], off
	v_lshl_add_u64 v[214:215], v[220:221], 0, s[74:75]
	s_mov_b32 m0, s56
	s_nop 0
	global_load_lds_dwordx4 v[214:215], off
	s_waitcnt vmcnt(8)
	s_waitcnt lgkmcnt(0)
	s_barrier
	s_waitcnt lgkmcnt(0)
	v_mfma_f32_16x16x32_bf16 v[78:81], v[58:61], v[176:179], v[78:81]
	v_mfma_f32_16x16x32_bf16 v[74:77], v[66:69], v[176:179], v[74:77]
	v_mfma_f32_16x16x32_bf16 v[46:49], v[58:61], v[186:189], v[46:49]
	v_mfma_f32_16x16x32_bf16 v[42:45], v[66:69], v[186:189], v[42:45]
	v_mfma_f32_16x16x32_bf16 v[30:33], v[58:61], v[194:197], v[30:33]
	v_mfma_f32_16x16x32_bf16 v[26:29], v[66:69], v[194:197], v[26:29]
	v_mfma_f32_16x16x32_bf16 v[14:17], v[58:61], v[202:205], v[14:17]
	v_mfma_f32_16x16x32_bf16 v[10:13], v[66:69], v[202:205], v[10:13]
	v_mfma_f32_16x16x32_bf16 v[78:81], v[62:65], v[180:183], v[78:81]
	v_mfma_f32_16x16x32_bf16 v[74:77], v[70:73], v[180:183], v[74:77]
	v_mfma_f32_16x16x32_bf16 v[46:49], v[62:65], v[190:193], v[46:49]
	v_mfma_f32_16x16x32_bf16 v[42:45], v[70:73], v[190:193], v[42:45]
	v_mfma_f32_16x16x32_bf16 v[30:33], v[62:65], v[198:201], v[30:33]
	v_mfma_f32_16x16x32_bf16 v[26:29], v[70:73], v[198:201], v[26:29]
	v_mfma_f32_16x16x32_bf16 v[14:17], v[62:65], v[206:209], v[14:17]
	v_mfma_f32_16x16x32_bf16 v[10:13], v[70:73], v[206:209], v[10:13]
	v_mfma_f32_16x16x32_bf16 v[50:53], v[90:93], v[176:179], v[50:53]
	v_mfma_f32_16x16x32_bf16 v[62:65], v[110:113], v[180:183], v[50:53]
	v_mfma_f32_16x16x32_bf16 v[50:53], v[126:129], v[176:179], v[54:57]
	v_mfma_f32_16x16x32_bf16 v[38:41], v[90:93], v[186:189], v[38:41]
	v_mfma_f32_16x16x32_bf16 v[34:37], v[126:129], v[186:189], v[34:37]
	v_mfma_f32_16x16x32_bf16 v[22:25], v[90:93], v[194:197], v[22:25]
	v_mfma_f32_16x16x32_bf16 v[18:21], v[126:129], v[194:197], v[18:21]
	v_mfma_f32_16x16x32_bf16 v[6:9], v[90:93], v[202:205], v[6:9]
	v_mfma_f32_16x16x32_bf16 v[2:5], v[126:129], v[202:205], v[2:5]
	v_mfma_f32_16x16x32_bf16 v[58:61], v[142:145], v[180:183], v[50:53]
	v_mfma_f32_16x16x32_bf16 v[38:41], v[110:113], v[190:193], v[38:41]
	v_mfma_f32_16x16x32_bf16 v[34:37], v[142:145], v[190:193], v[34:37]
	v_mfma_f32_16x16x32_bf16 v[22:25], v[110:113], v[198:201], v[22:25]
	v_mfma_f32_16x16x32_bf16 v[18:21], v[142:145], v[198:201], v[18:21]
	v_mfma_f32_16x16x32_bf16 v[6:9], v[110:113], v[206:209], v[6:9]
	v_mfma_f32_16x16x32_bf16 v[2:5], v[142:145], v[206:209], v[2:5]
	s_barrier
	s_add_i32 s62, s62, 2
	s_add_u32 s8, s8, 0x100
	s_addc_u32 s9, s9, 0
	s_add_u32 s33, s33, 0x100
	s_addc_u32 s61, s61, 0
	s_cmp_gt_u32 s62, 13
	s_cbranch_scc0 .LBB0_469
	s_and_b64 vcc, exec, s[28:29]
	s_cbranch_vccz .LBB0_472
	s_barrier

.LBB0_556:
	s_add_u32 s4, s26, 0x80
	s_addc_u32 s5, s27, 0
	s_add_u32 s26, s2, 0x100
	s_addc_u32 s27, s3, 0
	s_mov_b32 s2, 0
	s_add_i32 s33, s2, 2
	s_add_u32 s45, s4, 0x80
	s_addc_u32 s3, s5, 0
	s_add_i32 s48, 0, 0x10000
	s_cmp_eq_u32 s40, s2
	s_cselect_b32 s3, s23, s3
	s_cselect_b32 s2, s22, s45
	s_cselect_b32 s47, s25, s27
	s_cselect_b32 s46, s24, s26
	s_add_i32 s45, 0, 0x14000
	v_add_u32_e32 v70, s48, v199
	v_add_u32_e32 v158, s45, v199
	ds_read_b128 v[58:61], v70
	ds_read_b128 v[62:65], v70 offset:1024
	ds_read_b128 v[66:69], v70 offset:2048
	ds_read_b128 v[70:73], v70 offset:3072
	ds_read_b128 v[138:141], v158
	ds_read_b128 v[150:153], v158 offset:1024
	ds_read_b128 v[154:157], v158 offset:2048
	ds_read_b128 v[158:161], v158 offset:3072
	v_lshl_add_u64 v[196:197], s[4:5], 0, v[176:177]
	s_add_i32 m0, s30, 0xc000
	ds_read_b128 v[162:165], v201
	ds_read_b128 v[166:169], v201 offset:1024
	ds_read_b128 v[180:183], v201 offset:2048
	ds_read_b128 v[184:187], v201 offset:3072
	ds_read_b128 v[188:191], v201 offset:4096
	ds_read_b128 v[192:195], v201 offset:5120
	ds_read_b128 v[202:205], v201 offset:6144
	ds_read_b128 v[206:209], v201 offset:7168
	global_load_lds_dwordx4 v[196:197], off
	v_lshl_add_u64 v[196:197], s[4:5], 0, v[178:179]
	s_add_i32 m0, s30, 0xe000
	s_nop 0
	global_load_lds_dwordx4 v[196:197], off
	s_waitcnt vmcnt(8)
	s_waitcnt lgkmcnt(0)
	s_barrier
	s_waitcnt lgkmcnt(0)
	v_mfma_f32_16x16x32_bf16 v[146:149], v[58:61], v[162:165], 0
	v_mfma_f32_16x16x32_bf16 v[146:149], v[62:65], v[166:169], v[146:149]
	v_mfma_f32_16x16x32_bf16 v[134:137], v[138:141], v[162:165], 0
	v_mfma_f32_16x16x32_bf16 v[134:137], v[150:153], v[166:169], v[134:137]
	v_mfma_f32_16x16x32_bf16 v[142:145], v[66:69], v[162:165], 0
	v_mfma_f32_16x16x32_bf16 v[142:145], v[70:73], v[166:169], v[142:145]
	v_mfma_f32_16x16x32_bf16 v[130:133], v[154:157], v[162:165], 0
	v_mfma_f32_16x16x32_bf16 v[130:133], v[158:161], v[166:169], v[130:133]
	v_mfma_f32_16x16x32_bf16 v[126:129], v[58:61], v[180:183], 0
	v_mfma_f32_16x16x32_bf16 v[126:129], v[62:65], v[184:187], v[126:129]
	v_mfma_f32_16x16x32_bf16 v[118:121], v[138:141], v[180:183], 0
	v_mfma_f32_16x16x32_bf16 v[118:121], v[150:153], v[184:187], v[118:121]
	v_mfma_f32_16x16x32_bf16 v[122:125], v[66:69], v[180:183], 0
	v_mfma_f32_16x16x32_bf16 v[122:125], v[70:73], v[184:187], v[122:125]
	v_mfma_f32_16x16x32_bf16 v[114:117], v[154:157], v[180:183], 0
	v_mfma_f32_16x16x32_bf16 v[114:117], v[158:161], v[184:187], v[114:117]
	v_mfma_f32_16x16x32_bf16 v[110:113], v[58:61], v[188:191], 0
	v_mfma_f32_16x16x32_bf16 v[110:113], v[62:65], v[192:195], v[110:113]
	v_mfma_f32_16x16x32_bf16 v[102:105], v[138:141], v[188:191], 0
	v_mfma_f32_16x16x32_bf16 v[102:105], v[150:153], v[192:195], v[102:105]
	v_mfma_f32_16x16x32_bf16 v[106:109], v[66:69], v[188:191], 0
	v_mfma_f32_16x16x32_bf16 v[106:109], v[70:73], v[192:195], v[106:109]
	v_mfma_f32_16x16x32_bf16 v[98:101], v[154:157], v[188:191], 0
	v_mfma_f32_16x16x32_bf16 v[98:101], v[158:161], v[192:195], v[98:101]
	v_mfma_f32_16x16x32_bf16 v[94:97], v[58:61], v[202:205], 0
	v_mfma_f32_16x16x32_bf16 v[94:97], v[62:65], v[206:209], v[94:97]
	v_mfma_f32_16x16x32_bf16 v[86:89], v[138:141], v[202:205], 0
	v_mfma_f32_16x16x32_bf16 v[86:89], v[150:153], v[206:209], v[86:89]
	v_mfma_f32_16x16x32_bf16 v[90:93], v[66:69], v[202:205], 0
	v_mfma_f32_16x16x32_bf16 v[90:93], v[70:73], v[206:209], v[90:93]
	v_mfma_f32_16x16x32_bf16 v[82:85], v[154:157], v[202:205], 0
	v_mfma_f32_16x16x32_bf16 v[82:85], v[158:161], v[206:209], v[82:85]
	s_barrier
	s_add_i32 s48, s48, s29
	v_lshl_add_u64 v[196:197], s[46:47], 0, v[0:1]
	s_mov_b32 m0, s48
	ds_read_b128 v[162:165], v201 offset:16384
	ds_read_b128 v[166:169], v201 offset:17408
	ds_read_b128 v[180:183], v201 offset:18432
	ds_read_b128 v[184:187], v201 offset:19456
	ds_read_b128 v[188:191], v201 offset:20480
	ds_read_b128 v[192:195], v201 offset:21504
	ds_read_b128 v[202:205], v201 offset:22528
	ds_read_b128 v[206:209], v201 offset:23552
	global_load_lds_dwordx4 v[196:197], off
	s_add_i32 m0, s48, 0x2000
	v_lshl_add_u64 v[210:211], s[46:47], 0, v[170:171]
	s_add_u32 s46, s46, s12
	s_addc_u32 s47, s47, 0
	s_add_i32 s45, s45, s29
	global_load_lds_dwordx4 v[210:211], off
	v_lshl_add_u64 v[212:213], s[46:47], 0, v[0:1]
	s_mov_b32 m0, s45
	v_lshl_add_u64 v[214:215], s[46:47], 0, v[170:171]
	global_load_lds_dwordx4 v[212:213], off
	s_add_i32 m0, s45, 0x2000
	v_lshl_add_u64 v[216:217], s[2:3], 0, v[174:175]
	global_load_lds_dwordx4 v[214:215], off
	s_mov_b32 m0, s30
	v_lshl_add_u64 v[218:219], s[2:3], 0, v[172:173]
	global_load_lds_dwordx4 v[216:217], off
	s_mov_b32 m0, s31
	s_nop 0
	global_load_lds_dwordx4 v[218:219], off
	s_waitcnt vmcnt(8)
	s_waitcnt lgkmcnt(0)
	s_barrier
	s_waitcnt lgkmcnt(0)
	v_mfma_f32_16x16x32_bf16 v[78:81], v[58:61], v[162:165], 0
	v_mfma_f32_16x16x32_bf16 v[78:81], v[62:65], v[166:169], v[78:81]
	v_mfma_f32_16x16x32_bf16 v[54:57], v[138:141], v[162:165], 0
	v_mfma_f32_16x16x32_bf16 v[54:57], v[150:153], v[166:169], v[54:57]
	v_mfma_f32_16x16x32_bf16 v[74:77], v[66:69], v[162:165], 0
	v_mfma_f32_16x16x32_bf16 v[74:77], v[70:73], v[166:169], v[74:77]
	v_mfma_f32_16x16x32_bf16 v[50:53], v[154:157], v[162:165], 0
	v_mfma_f32_16x16x32_bf16 v[50:53], v[158:161], v[166:169], v[50:53]
	v_mfma_f32_16x16x32_bf16 v[46:49], v[58:61], v[180:183], 0
	v_mfma_f32_16x16x32_bf16 v[46:49], v[62:65], v[184:187], v[46:49]
	v_mfma_f32_16x16x32_bf16 v[38:41], v[138:141], v[180:183], 0
	v_mfma_f32_16x16x32_bf16 v[38:41], v[150:153], v[184:187], v[38:41]
	v_mfma_f32_16x16x32_bf16 v[42:45], v[66:69], v[180:183], 0
	v_mfma_f32_16x16x32_bf16 v[42:45], v[70:73], v[184:187], v[42:45]
	v_mfma_f32_16x16x32_bf16 v[34:37], v[154:157], v[180:183], 0
	v_mfma_f32_16x16x32_bf16 v[34:37], v[158:161], v[184:187], v[34:37]
	v_mfma_f32_16x16x32_bf16 v[30:33], v[58:61], v[188:191], 0
	v_mfma_f32_16x16x32_bf16 v[30:33], v[62:65], v[192:195], v[30:33]
	v_mfma_f32_16x16x32_bf16 v[22:25], v[138:141], v[188:191], 0
	v_mfma_f32_16x16x32_bf16 v[22:25], v[150:153], v[192:195], v[22:25]
	v_mfma_f32_16x16x32_bf16 v[26:29], v[66:69], v[188:191], 0
	v_mfma_f32_16x16x32_bf16 v[26:29], v[70:73], v[192:195], v[26:29]
	v_mfma_f32_16x16x32_bf16 v[18:21], v[154:157], v[188:191], 0
	v_mfma_f32_16x16x32_bf16 v[18:21], v[158:161], v[192:195], v[18:21]
	v_mfma_f32_16x16x32_bf16 v[14:17], v[58:61], v[202:205], 0
	v_mfma_f32_16x16x32_bf16 v[14:17], v[62:65], v[206:209], v[14:17]
	v_mfma_f32_16x16x32_bf16 v[6:9], v[138:141], v[202:205], 0
	v_mfma_f32_16x16x32_bf16 v[6:9], v[150:153], v[206:209], v[6:9]
	v_mfma_f32_16x16x32_bf16 v[10:13], v[66:69], v[202:205], 0
	v_mfma_f32_16x16x32_bf16 v[10:13], v[70:73], v[206:209], v[10:13]
	v_mfma_f32_16x16x32_bf16 v[2:5], v[154:157], v[202:205], 0
	v_mfma_f32_16x16x32_bf16 v[2:5], v[158:161], v[206:209], v[2:5]
	s_barrier
	s_add_i32 s45, 0, 0x18000
	s_add_i32 s46, 0, 0x1c000
	v_add_u32_e32 v70, s45, v199
	v_add_u32_e32 v158, s46, v199
	ds_read_b128 v[58:61], v70
	ds_read_b128 v[62:65], v70 offset:1024
	ds_read_b128 v[66:69], v70 offset:2048
	ds_read_b128 v[70:73], v70 offset:3072
	ds_read_b128 v[138:141], v158
	ds_read_b128 v[150:153], v158 offset:1024
	ds_read_b128 v[154:157], v158 offset:2048
	ds_read_b128 v[158:161], v158 offset:3072
	s_add_u32 s2, s2, s12
	s_addc_u32 s3, s3, 0
	s_mov_b32 m0, s34
	v_lshl_add_u64 v[220:221], s[2:3], 0, v[174:175]
	ds_read_b128 v[162:165], v201 offset:32768
	ds_read_b128 v[166:169], v201 offset:33792
	ds_read_b128 v[180:183], v201 offset:34816
	ds_read_b128 v[184:187], v201 offset:35840
	ds_read_b128 v[188:191], v201 offset:36864
	ds_read_b128 v[192:195], v201 offset:37888
	ds_read_b128 v[202:205], v201 offset:38912
	ds_read_b128 v[206:209], v201 offset:39936
	global_load_lds_dwordx4 v[220:221], off
	v_lshl_add_u64 v[220:221], s[2:3], 0, v[172:173]
	s_mov_b32 m0, s35
	s_nop 0
	global_load_lds_dwordx4 v[220:221], off
	s_waitcnt vmcnt(8)
	s_waitcnt lgkmcnt(0)
	s_barrier
	s_waitcnt lgkmcnt(0)
	v_mfma_f32_16x16x32_bf16 v[146:149], v[58:61], v[162:165], v[146:149]
	v_mfma_f32_16x16x32_bf16 v[146:149], v[62:65], v[166:169], v[146:149]
	v_mfma_f32_16x16x32_bf16 v[134:137], v[138:141], v[162:165], v[134:137]
	v_mfma_f32_16x16x32_bf16 v[134:137], v[150:153], v[166:169], v[134:137]
	v_mfma_f32_16x16x32_bf16 v[142:145], v[66:69], v[162:165], v[142:145]
	v_mfma_f32_16x16x32_bf16 v[142:145], v[70:73], v[166:169], v[142:145]
	v_mfma_f32_16x16x32_bf16 v[130:133], v[154:157], v[162:165], v[130:133]
	v_mfma_f32_16x16x32_bf16 v[130:133], v[158:161], v[166:169], v[130:133]
	v_mfma_f32_16x16x32_bf16 v[126:129], v[58:61], v[180:183], v[126:129]
	v_mfma_f32_16x16x32_bf16 v[126:129], v[62:65], v[184:187], v[126:129]
	v_mfma_f32_16x16x32_bf16 v[118:121], v[138:141], v[180:183], v[118:121]
	v_mfma_f32_16x16x32_bf16 v[118:121], v[150:153], v[184:187], v[118:121]
	v_mfma_f32_16x16x32_bf16 v[122:125], v[66:69], v[180:183], v[122:125]
	v_mfma_f32_16x16x32_bf16 v[122:125], v[70:73], v[184:187], v[122:125]
	v_mfma_f32_16x16x32_bf16 v[114:117], v[154:157], v[180:183], v[114:117]
	v_mfma_f32_16x16x32_bf16 v[114:117], v[158:161], v[184:187], v[114:117]
	v_mfma_f32_16x16x32_bf16 v[110:113], v[58:61], v[188:191], v[110:113]
	v_mfma_f32_16x16x32_bf16 v[110:113], v[62:65], v[192:195], v[110:113]
	v_mfma_f32_16x16x32_bf16 v[102:105], v[138:141], v[188:191], v[102:105]
	v_mfma_f32_16x16x32_bf16 v[102:105], v[150:153], v[192:195], v[102:105]
	v_mfma_f32_16x16x32_bf16 v[106:109], v[66:69], v[188:191], v[106:109]
	v_mfma_f32_16x16x32_bf16 v[106:109], v[70:73], v[192:195], v[106:109]
	v_mfma_f32_16x16x32_bf16 v[98:101], v[154:157], v[188:191], v[98:101]
	v_mfma_f32_16x16x32_bf16 v[98:101], v[158:161], v[192:195], v[98:101]
	v_mfma_f32_16x16x32_bf16 v[94:97], v[58:61], v[202:205], v[94:97]
	v_mfma_f32_16x16x32_bf16 v[94:97], v[62:65], v[206:209], v[94:97]
	v_mfma_f32_16x16x32_bf16 v[86:89], v[138:141], v[202:205], v[86:89]
	v_mfma_f32_16x16x32_bf16 v[86:89], v[150:153], v[206:209], v[86:89]
	v_mfma_f32_16x16x32_bf16 v[90:93], v[66:69], v[202:205], v[90:93]
	v_mfma_f32_16x16x32_bf16 v[90:93], v[70:73], v[206:209], v[90:93]
	v_mfma_f32_16x16x32_bf16 v[82:85], v[154:157], v[202:205], v[82:85]
	v_mfma_f32_16x16x32_bf16 v[82:85], v[158:161], v[206:209], v[82:85]
	s_barrier
	s_add_i32 s2, s45, s29
	v_lshl_add_u64 v[196:197], v[196:197], 0, s[74:75]
	s_mov_b32 m0, s2
	ds_read_b128 v[162:165], v201 offset:49152
	ds_read_b128 v[166:169], v201 offset:50176
	ds_read_b128 v[180:183], v201 offset:51200
	ds_read_b128 v[184:187], v201 offset:52224
	ds_read_b128 v[188:191], v201 offset:53248
	ds_read_b128 v[192:195], v201 offset:54272
	ds_read_b128 v[202:205], v201 offset:55296
	ds_read_b128 v[206:209], v201 offset:56320
	global_load_lds_dwordx4 v[196:197], off
	v_lshl_add_u64 v[196:197], v[210:211], 0, s[74:75]
	s_add_i32 m0, s2, 0x2000
	s_add_i32 s2, s46, s29
	global_load_lds_dwordx4 v[196:197], off
	v_lshl_add_u64 v[196:197], v[212:213], 0, s[74:75]
	s_mov_b32 m0, s2
	s_nop 0
	global_load_lds_dwordx4 v[196:197], off
	v_lshl_add_u64 v[196:197], v[214:215], 0, s[74:75]
	s_add_i32 m0, s2, 0x2000
	s_nop 0
	global_load_lds_dwordx4 v[196:197], off
	v_lshl_add_u64 v[196:197], v[216:217], 0, s[74:75]
	s_mov_b32 m0, s38
	s_nop 0
	global_load_lds_dwordx4 v[196:197], off
	v_lshl_add_u64 v[196:197], v[218:219], 0, s[74:75]
	s_mov_b32 m0, s39
	s_nop 0
	global_load_lds_dwordx4 v[196:197], off
	s_waitcnt vmcnt(8)
	s_waitcnt lgkmcnt(0)
	s_barrier
	s_waitcnt lgkmcnt(0)
	v_mfma_f32_16x16x32_bf16 v[78:81], v[58:61], v[162:165], v[78:81]
	v_mfma_f32_16x16x32_bf16 v[78:81], v[62:65], v[166:169], v[78:81]
	v_mfma_f32_16x16x32_bf16 v[54:57], v[138:141], v[162:165], v[54:57]
	v_mfma_f32_16x16x32_bf16 v[54:57], v[150:153], v[166:169], v[54:57]
	v_mfma_f32_16x16x32_bf16 v[74:77], v[66:69], v[162:165], v[74:77]
	v_mfma_f32_16x16x32_bf16 v[74:77], v[70:73], v[166:169], v[74:77]
	v_mfma_f32_16x16x32_bf16 v[50:53], v[154:157], v[162:165], v[50:53]
	v_mfma_f32_16x16x32_bf16 v[50:53], v[158:161], v[166:169], v[50:53]
	v_mfma_f32_16x16x32_bf16 v[46:49], v[58:61], v[180:183], v[46:49]
	v_mfma_f32_16x16x32_bf16 v[46:49], v[62:65], v[184:187], v[46:49]
	v_mfma_f32_16x16x32_bf16 v[38:41], v[138:141], v[180:183], v[38:41]
	v_mfma_f32_16x16x32_bf16 v[38:41], v[150:153], v[184:187], v[38:41]
	v_mfma_f32_16x16x32_bf16 v[42:45], v[66:69], v[180:183], v[42:45]
	v_mfma_f32_16x16x32_bf16 v[42:45], v[70:73], v[184:187], v[42:45]
	v_mfma_f32_16x16x32_bf16 v[34:37], v[154:157], v[180:183], v[34:37]
	v_mfma_f32_16x16x32_bf16 v[34:37], v[158:161], v[184:187], v[34:37]
	v_mfma_f32_16x16x32_bf16 v[30:33], v[58:61], v[188:191], v[30:33]
	v_mfma_f32_16x16x32_bf16 v[30:33], v[62:65], v[192:195], v[30:33]
	v_mfma_f32_16x16x32_bf16 v[22:25], v[138:141], v[188:191], v[22:25]
	v_mfma_f32_16x16x32_bf16 v[22:25], v[150:153], v[192:195], v[22:25]
	v_mfma_f32_16x16x32_bf16 v[26:29], v[66:69], v[188:191], v[26:29]
	v_mfma_f32_16x16x32_bf16 v[26:29], v[70:73], v[192:195], v[26:29]
	v_mfma_f32_16x16x32_bf16 v[18:21], v[154:157], v[188:191], v[18:21]
	v_mfma_f32_16x16x32_bf16 v[18:21], v[158:161], v[192:195], v[18:21]
	v_mfma_f32_16x16x32_bf16 v[14:17], v[58:61], v[202:205], v[14:17]
	v_mfma_f32_16x16x32_bf16 v[14:17], v[62:65], v[206:209], v[14:17]
	v_mfma_f32_16x16x32_bf16 v[6:9], v[138:141], v[202:205], v[6:9]
	v_mfma_f32_16x16x32_bf16 v[6:9], v[150:153], v[206:209], v[6:9]
	v_mfma_f32_16x16x32_bf16 v[10:13], v[66:69], v[202:205], v[10:13]
	v_mfma_f32_16x16x32_bf16 v[10:13], v[70:73], v[206:209], v[10:13]
	v_mfma_f32_16x16x32_bf16 v[2:5], v[154:157], v[202:205], v[2:5]
	v_mfma_f32_16x16x32_bf16 v[2:5], v[158:161], v[206:209], v[2:5]
	s_barrier
	s_add_u32 s4, s4, 0x100
	s_addc_u32 s5, s5, 0
	s_add_u32 s26, s26, 0x100
	s_addc_u32 s27, s27, 0
	s_cmp_ge_u32 s33, s37
	s_mov_b32 s2, s33
.LBB0_557:
	s_add_i32 s33, s2, 2
	s_add_u32 s45, s4, 0x80
	s_addc_u32 s3, s5, 0
	s_add_i32 s48, 0, 0x10000
	s_cmp_eq_u32 s40, s2
	s_cselect_b32 s3, s23, s3
	s_cselect_b32 s2, s22, s45
	s_cselect_b32 s47, s25, s27
	s_cselect_b32 s46, s24, s26
	s_add_i32 s45, 0, 0x14000
	v_add_u32_e32 v70, s48, v199
	v_add_u32_e32 v158, s45, v199
	ds_read_b128 v[58:61], v70
	ds_read_b128 v[62:65], v70 offset:1024
	ds_read_b128 v[66:69], v70 offset:2048
	ds_read_b128 v[70:73], v70 offset:3072
	ds_read_b128 v[138:141], v158
	ds_read_b128 v[150:153], v158 offset:1024
	ds_read_b128 v[154:157], v158 offset:2048
	ds_read_b128 v[158:161], v158 offset:3072
	v_lshl_add_u64 v[196:197], s[4:5], 0, v[176:177]
	s_add_i32 m0, s30, 0xc000
	ds_read_b128 v[162:165], v201
	ds_read_b128 v[166:169], v201 offset:1024
	ds_read_b128 v[180:183], v201 offset:2048
	ds_read_b128 v[184:187], v201 offset:3072
	ds_read_b128 v[188:191], v201 offset:4096
	ds_read_b128 v[192:195], v201 offset:5120
	ds_read_b128 v[202:205], v201 offset:6144
	ds_read_b128 v[206:209], v201 offset:7168
	global_load_lds_dwordx4 v[196:197], off
	v_lshl_add_u64 v[196:197], s[4:5], 0, v[178:179]
	s_add_i32 m0, s30, 0xe000
	s_nop 0
	global_load_lds_dwordx4 v[196:197], off
	s_waitcnt vmcnt(8)
	s_waitcnt lgkmcnt(0)
	s_barrier
	s_waitcnt lgkmcnt(0)
	v_mfma_f32_16x16x32_bf16 v[146:149], v[58:61], v[162:165], v[146:149]
	v_mfma_f32_16x16x32_bf16 v[146:149], v[62:65], v[166:169], v[146:149]
	v_mfma_f32_16x16x32_bf16 v[134:137], v[138:141], v[162:165], v[134:137]
	v_mfma_f32_16x16x32_bf16 v[134:137], v[150:153], v[166:169], v[134:137]
	v_mfma_f32_16x16x32_bf16 v[142:145], v[66:69], v[162:165], v[142:145]
	v_mfma_f32_16x16x32_bf16 v[142:145], v[70:73], v[166:169], v[142:145]
	v_mfma_f32_16x16x32_bf16 v[130:133], v[154:157], v[162:165], v[130:133]
	v_mfma_f32_16x16x32_bf16 v[130:133], v[158:161], v[166:169], v[130:133]
	v_mfma_f32_16x16x32_bf16 v[126:129], v[58:61], v[180:183], v[126:129]
	v_mfma_f32_16x16x32_bf16 v[126:129], v[62:65], v[184:187], v[126:129]
	v_mfma_f32_16x16x32_bf16 v[118:121], v[138:141], v[180:183], v[118:121]
	v_mfma_f32_16x16x32_bf16 v[118:121], v[150:153], v[184:187], v[118:121]
	v_mfma_f32_16x16x32_bf16 v[122:125], v[66:69], v[180:183], v[122:125]
	v_mfma_f32_16x16x32_bf16 v[122:125], v[70:73], v[184:187], v[122:125]
	v_mfma_f32_16x16x32_bf16 v[114:117], v[154:157], v[180:183], v[114:117]
	v_mfma_f32_16x16x32_bf16 v[114:117], v[158:161], v[184:187], v[114:117]
	v_mfma_f32_16x16x32_bf16 v[110:113], v[58:61], v[188:191], v[110:113]
	v_mfma_f32_16x16x32_bf16 v[110:113], v[62:65], v[192:195], v[110:113]
	v_mfma_f32_16x16x32_bf16 v[102:105], v[138:141], v[188:191], v[102:105]
	v_mfma_f32_16x16x32_bf16 v[102:105], v[150:153], v[192:195], v[102:105]
	v_mfma_f32_16x16x32_bf16 v[106:109], v[66:69], v[188:191], v[106:109]
	v_mfma_f32_16x16x32_bf16 v[106:109], v[70:73], v[192:195], v[106:109]
	v_mfma_f32_16x16x32_bf16 v[98:101], v[154:157], v[188:191], v[98:101]
	v_mfma_f32_16x16x32_bf16 v[98:101], v[158:161], v[192:195], v[98:101]
	v_mfma_f32_16x16x32_bf16 v[94:97], v[58:61], v[202:205], v[94:97]
	v_mfma_f32_16x16x32_bf16 v[94:97], v[62:65], v[206:209], v[94:97]
	v_mfma_f32_16x16x32_bf16 v[86:89], v[138:141], v[202:205], v[86:89]
	v_mfma_f32_16x16x32_bf16 v[86:89], v[150:153], v[206:209], v[86:89]
	v_mfma_f32_16x16x32_bf16 v[90:93], v[66:69], v[202:205], v[90:93]
	v_mfma_f32_16x16x32_bf16 v[90:93], v[70:73], v[206:209], v[90:93]
	v_mfma_f32_16x16x32_bf16 v[82:85], v[154:157], v[202:205], v[82:85]
	v_mfma_f32_16x16x32_bf16 v[82:85], v[158:161], v[206:209], v[82:85]
	s_barrier
	s_add_i32 s48, s48, s29
	v_lshl_add_u64 v[196:197], s[46:47], 0, v[0:1]
	s_mov_b32 m0, s48
	ds_read_b128 v[162:165], v201 offset:16384
	ds_read_b128 v[166:169], v201 offset:17408
	ds_read_b128 v[180:183], v201 offset:18432
	ds_read_b128 v[184:187], v201 offset:19456
	ds_read_b128 v[188:191], v201 offset:20480
	ds_read_b128 v[192:195], v201 offset:21504
	ds_read_b128 v[202:205], v201 offset:22528
	ds_read_b128 v[206:209], v201 offset:23552
	global_load_lds_dwordx4 v[196:197], off
	s_add_i32 m0, s48, 0x2000
	v_lshl_add_u64 v[210:211], s[46:47], 0, v[170:171]
	s_add_u32 s46, s46, s12
	s_addc_u32 s47, s47, 0
	s_add_i32 s45, s45, s29
	global_load_lds_dwordx4 v[210:211], off
	v_lshl_add_u64 v[212:213], s[46:47], 0, v[0:1]
	s_mov_b32 m0, s45
	v_lshl_add_u64 v[214:215], s[46:47], 0, v[170:171]
	global_load_lds_dwordx4 v[212:213], off
	s_add_i32 m0, s45, 0x2000
	v_lshl_add_u64 v[216:217], s[2:3], 0, v[174:175]
	global_load_lds_dwordx4 v[214:215], off
	s_mov_b32 m0, s30
	v_lshl_add_u64 v[218:219], s[2:3], 0, v[172:173]
	global_load_lds_dwordx4 v[216:217], off
	s_mov_b32 m0, s31
	s_nop 0
	global_load_lds_dwordx4 v[218:219], off
	s_waitcnt vmcnt(8)
	s_waitcnt lgkmcnt(0)
	s_barrier
	s_waitcnt lgkmcnt(0)
	v_mfma_f32_16x16x32_bf16 v[78:81], v[58:61], v[162:165], v[78:81]
	v_mfma_f32_16x16x32_bf16 v[78:81], v[62:65], v[166:169], v[78:81]
	v_mfma_f32_16x16x32_bf16 v[54:57], v[138:141], v[162:165], v[54:57]
	v_mfma_f32_16x16x32_bf16 v[54:57], v[150:153], v[166:169], v[54:57]
	v_mfma_f32_16x16x32_bf16 v[74:77], v[66:69], v[162:165], v[74:77]
	v_mfma_f32_16x16x32_bf16 v[74:77], v[70:73], v[166:169], v[74:77]
	v_mfma_f32_16x16x32_bf16 v[50:53], v[154:157], v[162:165], v[50:53]
	v_mfma_f32_16x16x32_bf16 v[50:53], v[158:161], v[166:169], v[50:53]
	v_mfma_f32_16x16x32_bf16 v[46:49], v[58:61], v[180:183], v[46:49]
	v_mfma_f32_16x16x32_bf16 v[46:49], v[62:65], v[184:187], v[46:49]
	v_mfma_f32_16x16x32_bf16 v[38:41], v[138:141], v[180:183], v[38:41]
	v_mfma_f32_16x16x32_bf16 v[38:41], v[150:153], v[184:187], v[38:41]
	v_mfma_f32_16x16x32_bf16 v[42:45], v[66:69], v[180:183], v[42:45]
	v_mfma_f32_16x16x32_bf16 v[42:45], v[70:73], v[184:187], v[42:45]
	v_mfma_f32_16x16x32_bf16 v[34:37], v[154:157], v[180:183], v[34:37]
	v_mfma_f32_16x16x32_bf16 v[34:37], v[158:161], v[184:187], v[34:37]
	v_mfma_f32_16x16x32_bf16 v[30:33], v[58:61], v[188:191], v[30:33]
	v_mfma_f32_16x16x32_bf16 v[30:33], v[62:65], v[192:195], v[30:33]
	v_mfma_f32_16x16x32_bf16 v[22:25], v[138:141], v[188:191], v[22:25]
	v_mfma_f32_16x16x32_bf16 v[22:25], v[150:153], v[192:195], v[22:25]
	v_mfma_f32_16x16x32_bf16 v[26:29], v[66:69], v[188:191], v[26:29]
	v_mfma_f32_16x16x32_bf16 v[26:29], v[70:73], v[192:195], v[26:29]
	v_mfma_f32_16x16x32_bf16 v[18:21], v[154:157], v[188:191], v[18:21]
	v_mfma_f32_16x16x32_bf16 v[18:21], v[158:161], v[192:195], v[18:21]
	v_mfma_f32_16x16x32_bf16 v[14:17], v[58:61], v[202:205], v[14:17]
	v_mfma_f32_16x16x32_bf16 v[14:17], v[62:65], v[206:209], v[14:17]
	v_mfma_f32_16x16x32_bf16 v[6:9], v[138:141], v[202:205], v[6:9]
	v_mfma_f32_16x16x32_bf16 v[6:9], v[150:153], v[206:209], v[6:9]
	v_mfma_f32_16x16x32_bf16 v[10:13], v[66:69], v[202:205], v[10:13]
	v_mfma_f32_16x16x32_bf16 v[10:13], v[70:73], v[206:209], v[10:13]
	v_mfma_f32_16x16x32_bf16 v[2:5], v[154:157], v[202:205], v[2:5]
	v_mfma_f32_16x16x32_bf16 v[2:5], v[158:161], v[206:209], v[2:5]
	s_barrier
	s_add_i32 s45, 0, 0x18000
	s_add_i32 s46, 0, 0x1c000
	v_add_u32_e32 v70, s45, v199
	v_add_u32_e32 v158, s46, v199
	ds_read_b128 v[58:61], v70
	ds_read_b128 v[62:65], v70 offset:1024
	ds_read_b128 v[66:69], v70 offset:2048
	ds_read_b128 v[70:73], v70 offset:3072
	ds_read_b128 v[138:141], v158
	ds_read_b128 v[150:153], v158 offset:1024
	ds_read_b128 v[154:157], v158 offset:2048
	ds_read_b128 v[158:161], v158 offset:3072
	s_add_u32 s2, s2, s12
	s_addc_u32 s3, s3, 0
	s_mov_b32 m0, s34
	v_lshl_add_u64 v[220:221], s[2:3], 0, v[174:175]
	ds_read_b128 v[162:165], v201 offset:32768
	ds_read_b128 v[166:169], v201 offset:33792
	ds_read_b128 v[180:183], v201 offset:34816
	ds_read_b128 v[184:187], v201 offset:35840
	ds_read_b128 v[188:191], v201 offset:36864
	ds_read_b128 v[192:195], v201 offset:37888
	ds_read_b128 v[202:205], v201 offset:38912
	ds_read_b128 v[206:209], v201 offset:39936
	global_load_lds_dwordx4 v[220:221], off
	v_lshl_add_u64 v[220:221], s[2:3], 0, v[172:173]
	s_mov_b32 m0, s35
	s_nop 0
	global_load_lds_dwordx4 v[220:221], off
	s_waitcnt vmcnt(8)
	s_waitcnt lgkmcnt(0)
	s_barrier
	s_waitcnt lgkmcnt(0)
	v_mfma_f32_16x16x32_bf16 v[146:149], v[58:61], v[162:165], v[146:149]
	v_mfma_f32_16x16x32_bf16 v[146:149], v[62:65], v[166:169], v[146:149]
	v_mfma_f32_16x16x32_bf16 v[134:137], v[138:141], v[162:165], v[134:137]
	v_mfma_f32_16x16x32_bf16 v[134:137], v[150:153], v[166:169], v[134:137]
	v_mfma_f32_16x16x32_bf16 v[142:145], v[66:69], v[162:165], v[142:145]
	v_mfma_f32_16x16x32_bf16 v[142:145], v[70:73], v[166:169], v[142:145]
	v_mfma_f32_16x16x32_bf16 v[130:133], v[154:157], v[162:165], v[130:133]
	v_mfma_f32_16x16x32_bf16 v[130:133], v[158:161], v[166:169], v[130:133]
	v_mfma_f32_16x16x32_bf16 v[126:129], v[58:61], v[180:183], v[126:129]
	v_mfma_f32_16x16x32_bf16 v[126:129], v[62:65], v[184:187], v[126:129]
	v_mfma_f32_16x16x32_bf16 v[118:121], v[138:141], v[180:183], v[118:121]
	v_mfma_f32_16x16x32_bf16 v[118:121], v[150:153], v[184:187], v[118:121]
	v_mfma_f32_16x16x32_bf16 v[122:125], v[66:69], v[180:183], v[122:125]
	v_mfma_f32_16x16x32_bf16 v[122:125], v[70:73], v[184:187], v[122:125]
	v_mfma_f32_16x16x32_bf16 v[114:117], v[154:157], v[180:183], v[114:117]
	v_mfma_f32_16x16x32_bf16 v[114:117], v[158:161], v[184:187], v[114:117]
	v_mfma_f32_16x16x32_bf16 v[110:113], v[58:61], v[188:191], v[110:113]
	v_mfma_f32_16x16x32_bf16 v[110:113], v[62:65], v[192:195], v[110:113]
	v_mfma_f32_16x16x32_bf16 v[102:105], v[138:141], v[188:191], v[102:105]
	v_mfma_f32_16x16x32_bf16 v[102:105], v[150:153], v[192:195], v[102:105]
	v_mfma_f32_16x16x32_bf16 v[106:109], v[66:69], v[188:191], v[106:109]
	v_mfma_f32_16x16x32_bf16 v[106:109], v[70:73], v[192:195], v[106:109]
	v_mfma_f32_16x16x32_bf16 v[98:101], v[154:157], v[188:191], v[98:101]
	v_mfma_f32_16x16x32_bf16 v[98:101], v[158:161], v[192:195], v[98:101]
	v_mfma_f32_16x16x32_bf16 v[94:97], v[58:61], v[202:205], v[94:97]
	v_mfma_f32_16x16x32_bf16 v[94:97], v[62:65], v[206:209], v[94:97]
	v_mfma_f32_16x16x32_bf16 v[86:89], v[138:141], v[202:205], v[86:89]
	v_mfma_f32_16x16x32_bf16 v[86:89], v[150:153], v[206:209], v[86:89]
	v_mfma_f32_16x16x32_bf16 v[90:93], v[66:69], v[202:205], v[90:93]
	v_mfma_f32_16x16x32_bf16 v[90:93], v[70:73], v[206:209], v[90:93]
	v_mfma_f32_16x16x32_bf16 v[82:85], v[154:157], v[202:205], v[82:85]
	v_mfma_f32_16x16x32_bf16 v[82:85], v[158:161], v[206:209], v[82:85]
	s_barrier
	s_add_i32 s2, s45, s29
	v_lshl_add_u64 v[196:197], v[196:197], 0, s[74:75]
	s_mov_b32 m0, s2
	ds_read_b128 v[162:165], v201 offset:49152
	ds_read_b128 v[166:169], v201 offset:50176
	ds_read_b128 v[180:183], v201 offset:51200
	ds_read_b128 v[184:187], v201 offset:52224
	ds_read_b128 v[188:191], v201 offset:53248
	ds_read_b128 v[192:195], v201 offset:54272
	ds_read_b128 v[202:205], v201 offset:55296
	ds_read_b128 v[206:209], v201 offset:56320
	global_load_lds_dwordx4 v[196:197], off
	v_lshl_add_u64 v[196:197], v[210:211], 0, s[74:75]
	s_add_i32 m0, s2, 0x2000
	s_add_i32 s2, s46, s29
	global_load_lds_dwordx4 v[196:197], off
	v_lshl_add_u64 v[196:197], v[212:213], 0, s[74:75]
	s_mov_b32 m0, s2
	s_nop 0
	global_load_lds_dwordx4 v[196:197], off
	v_lshl_add_u64 v[196:197], v[214:215], 0, s[74:75]
	s_add_i32 m0, s2, 0x2000
	s_nop 0
	global_load_lds_dwordx4 v[196:197], off
	v_lshl_add_u64 v[196:197], v[216:217], 0, s[74:75]
	s_mov_b32 m0, s38
	s_nop 0
	global_load_lds_dwordx4 v[196:197], off
	v_lshl_add_u64 v[196:197], v[218:219], 0, s[74:75]
	s_mov_b32 m0, s39
	s_nop 0
	global_load_lds_dwordx4 v[196:197], off
	s_waitcnt vmcnt(8)
	s_waitcnt lgkmcnt(0)
	s_barrier
	s_waitcnt lgkmcnt(0)
	v_mfma_f32_16x16x32_bf16 v[78:81], v[58:61], v[162:165], v[78:81]
	v_mfma_f32_16x16x32_bf16 v[78:81], v[62:65], v[166:169], v[78:81]
	v_mfma_f32_16x16x32_bf16 v[54:57], v[138:141], v[162:165], v[54:57]
	v_mfma_f32_16x16x32_bf16 v[54:57], v[150:153], v[166:169], v[54:57]
	v_mfma_f32_16x16x32_bf16 v[74:77], v[66:69], v[162:165], v[74:77]
	v_mfma_f32_16x16x32_bf16 v[74:77], v[70:73], v[166:169], v[74:77]
	v_mfma_f32_16x16x32_bf16 v[50:53], v[154:157], v[162:165], v[50:53]
	v_mfma_f32_16x16x32_bf16 v[50:53], v[158:161], v[166:169], v[50:53]
	v_mfma_f32_16x16x32_bf16 v[46:49], v[58:61], v[180:183], v[46:49]
	v_mfma_f32_16x16x32_bf16 v[46:49], v[62:65], v[184:187], v[46:49]
	v_mfma_f32_16x16x32_bf16 v[38:41], v[138:141], v[180:183], v[38:41]
	v_mfma_f32_16x16x32_bf16 v[38:41], v[150:153], v[184:187], v[38:41]
	v_mfma_f32_16x16x32_bf16 v[42:45], v[66:69], v[180:183], v[42:45]
	v_mfma_f32_16x16x32_bf16 v[42:45], v[70:73], v[184:187], v[42:45]
	v_mfma_f32_16x16x32_bf16 v[34:37], v[154:157], v[180:183], v[34:37]
	v_mfma_f32_16x16x32_bf16 v[34:37], v[158:161], v[184:187], v[34:37]
	v_mfma_f32_16x16x32_bf16 v[30:33], v[58:61], v[188:191], v[30:33]
	v_mfma_f32_16x16x32_bf16 v[30:33], v[62:65], v[192:195], v[30:33]
	v_mfma_f32_16x16x32_bf16 v[22:25], v[138:141], v[188:191], v[22:25]
	v_mfma_f32_16x16x32_bf16 v[22:25], v[150:153], v[192:195], v[22:25]
	v_mfma_f32_16x16x32_bf16 v[26:29], v[66:69], v[188:191], v[26:29]
	v_mfma_f32_16x16x32_bf16 v[26:29], v[70:73], v[192:195], v[26:29]
	v_mfma_f32_16x16x32_bf16 v[18:21], v[154:157], v[188:191], v[18:21]
	v_mfma_f32_16x16x32_bf16 v[18:21], v[158:161], v[192:195], v[18:21]
	v_mfma_f32_16x16x32_bf16 v[14:17], v[58:61], v[202:205], v[14:17]
	v_mfma_f32_16x16x32_bf16 v[14:17], v[62:65], v[206:209], v[14:17]
	v_mfma_f32_16x16x32_bf16 v[6:9], v[138:141], v[202:205], v[6:9]
	v_mfma_f32_16x16x32_bf16 v[6:9], v[150:153], v[206:209], v[6:9]
	v_mfma_f32_16x16x32_bf16 v[10:13], v[66:69], v[202:205], v[10:13]
	v_mfma_f32_16x16x32_bf16 v[10:13], v[70:73], v[206:209], v[10:13]
	v_mfma_f32_16x16x32_bf16 v[2:5], v[154:157], v[202:205], v[2:5]
	v_mfma_f32_16x16x32_bf16 v[2:5], v[158:161], v[206:209], v[2:5]
	s_barrier
	s_add_u32 s4, s4, 0x100
	s_addc_u32 s5, s5, 0
	s_add_u32 s26, s26, 0x100
	s_addc_u32 s27, s27, 0
	s_cmp_ge_u32 s33, s37
	s_mov_b32 s2, s33
	s_cbranch_scc0 .LBB0_557
	s_and_b64 vcc, exec, s[18:19]
	s_cbranch_vccz .LBB0_560
	s_barrier

.LBB0_597:
	s_ashr_i32 s9, s8, 31
	s_lshl_b64 s[12:13], s[8:9], 19
	s_add_u32 s12, s82, s12
	s_addc_u32 s13, s83, s13
	s_and_b64 s[14:15], s[0:1], exec
	s_cselect_b32 s9, s13, s17
	s_cselect_b32 s34, s12, s16
	s_ashr_i32 s11, s10, 31
	s_lshl_b64 s[14:15], s[10:11], 19
	s_add_u32 s14, s20, s14
	s_addc_u32 s15, s21, s15
	s_and_b64 s[18:19], s[0:1], exec
	s_cselect_b32 s11, s15, s3
	s_cselect_b32 s35, s14, s2
	s_add_u32 s16, s16, 0x40080
	s_addc_u32 s17, s17, 0
	s_add_u32 s33, s2, 0x100
	s_addc_u32 s36, s3, 0
	s_mov_b32 s37, -2
	s_add_u32 s2, s16, 0xfffc0080
	s_addc_u32 s3, s17, -1
	s_add_i32 s38, 0, 0x10000
	s_cmp_eq_u32 s37, 12
	s_cselect_b32 s19, s9, s3
	s_cselect_b32 s18, s34, s2
	s_cselect_b32 s3, s11, s36
	s_cselect_b32 s2, s35, s33
	s_add_i32 s40, 0, 0x14000
	v_add_u32_e32 v154, s38, v159
	v_add_u32_e32 v174, s40, v159
	ds_read_b128 v[142:145], v154
	ds_read_b128 v[146:149], v154 offset:1024
	ds_read_b128 v[150:153], v154 offset:2048
	ds_read_b128 v[154:157], v154 offset:3072
	ds_read_b128 v[162:165], v174
	ds_read_b128 v[166:169], v174 offset:1024
	ds_read_b128 v[170:173], v174 offset:2048
	ds_read_b128 v[174:177], v174 offset:3072
	v_lshl_add_u64 v[210:211], s[16:17], 0, v[138:139]
	s_add_i32 m0, s23, 0xc000
	ds_read_b128 v[178:181], v161
	ds_read_b128 v[182:185], v161 offset:1024
	ds_read_b128 v[186:189], v161 offset:2048
	ds_read_b128 v[190:193], v161 offset:3072
	ds_read_b128 v[194:197], v161 offset:4096
	ds_read_b128 v[198:201], v161 offset:5120
	ds_read_b128 v[202:205], v161 offset:6144
	ds_read_b128 v[206:209], v161 offset:7168
	global_load_lds_dwordx4 v[210:211], off
	v_lshl_add_u64 v[210:211], s[16:17], 0, v[140:141]
	s_add_i32 m0, s23, 0xe000
	s_nop 0
	global_load_lds_dwordx4 v[210:211], off
	s_waitcnt vmcnt(8)
	s_waitcnt lgkmcnt(0)
	s_barrier
	s_waitcnt lgkmcnt(0)
	v_mfma_f32_16x16x32_bf16 v[126:129], v[142:145], v[178:181], 0
	v_mfma_f32_16x16x32_bf16 v[126:129], v[146:149], v[182:185], v[126:129]
	v_mfma_f32_16x16x32_bf16 v[122:125], v[162:165], v[178:181], 0
	v_mfma_f32_16x16x32_bf16 v[122:125], v[166:169], v[182:185], v[122:125]
	v_mfma_f32_16x16x32_bf16 v[118:121], v[150:153], v[178:181], 0
	v_mfma_f32_16x16x32_bf16 v[118:121], v[154:157], v[182:185], v[118:121]
	v_mfma_f32_16x16x32_bf16 v[114:117], v[170:173], v[178:181], 0
	v_mfma_f32_16x16x32_bf16 v[114:117], v[174:177], v[182:185], v[114:117]
	v_mfma_f32_16x16x32_bf16 v[110:113], v[142:145], v[186:189], 0
	v_mfma_f32_16x16x32_bf16 v[110:113], v[146:149], v[190:193], v[110:113]
	v_mfma_f32_16x16x32_bf16 v[106:109], v[162:165], v[186:189], 0
	v_mfma_f32_16x16x32_bf16 v[106:109], v[166:169], v[190:193], v[106:109]
	v_mfma_f32_16x16x32_bf16 v[102:105], v[150:153], v[186:189], 0
	v_mfma_f32_16x16x32_bf16 v[102:105], v[154:157], v[190:193], v[102:105]
	v_mfma_f32_16x16x32_bf16 v[98:101], v[170:173], v[186:189], 0
	v_mfma_f32_16x16x32_bf16 v[98:101], v[174:177], v[190:193], v[98:101]
	v_mfma_f32_16x16x32_bf16 v[94:97], v[142:145], v[194:197], 0
	v_mfma_f32_16x16x32_bf16 v[94:97], v[146:149], v[198:201], v[94:97]
	v_mfma_f32_16x16x32_bf16 v[90:93], v[162:165], v[194:197], 0
	v_mfma_f32_16x16x32_bf16 v[90:93], v[166:169], v[198:201], v[90:93]
	v_mfma_f32_16x16x32_bf16 v[86:89], v[150:153], v[194:197], 0
	v_mfma_f32_16x16x32_bf16 v[86:89], v[154:157], v[198:201], v[86:89]
	v_mfma_f32_16x16x32_bf16 v[82:85], v[170:173], v[194:197], 0
	v_mfma_f32_16x16x32_bf16 v[82:85], v[174:177], v[198:201], v[82:85]
	v_mfma_f32_16x16x32_bf16 v[78:81], v[142:145], v[202:205], 0
	v_mfma_f32_16x16x32_bf16 v[78:81], v[146:149], v[206:209], v[78:81]
	v_mfma_f32_16x16x32_bf16 v[74:77], v[162:165], v[202:205], 0
	v_mfma_f32_16x16x32_bf16 v[74:77], v[166:169], v[206:209], v[74:77]
	v_mfma_f32_16x16x32_bf16 v[70:73], v[150:153], v[202:205], 0
	v_mfma_f32_16x16x32_bf16 v[70:73], v[154:157], v[206:209], v[70:73]
	v_mfma_f32_16x16x32_bf16 v[66:69], v[170:173], v[202:205], 0
	v_mfma_f32_16x16x32_bf16 v[66:69], v[174:177], v[206:209], v[66:69]
	s_barrier
	s_add_i32 s38, s38, s22
	v_lshl_add_u64 v[210:211], s[2:3], 0, v[0:1]
	s_mov_b32 m0, s38
	ds_read_b128 v[178:181], v161 offset:16384
	ds_read_b128 v[182:185], v161 offset:17408
	ds_read_b128 v[186:189], v161 offset:18432
	ds_read_b128 v[190:193], v161 offset:19456
	ds_read_b128 v[194:197], v161 offset:20480
	ds_read_b128 v[198:201], v161 offset:21504
	ds_read_b128 v[202:205], v161 offset:22528
	ds_read_b128 v[206:209], v161 offset:23552
	global_load_lds_dwordx4 v[210:211], off
	s_add_i32 m0, s38, 0x2000
	s_add_u32 s38, s2, 0x40000
	v_lshl_add_u64 v[212:213], s[2:3], 0, v[130:131]
	s_addc_u32 s39, s3, 0
	s_add_i32 s40, s40, s22
	global_load_lds_dwordx4 v[212:213], off
	v_lshl_add_u64 v[214:215], s[38:39], 0, v[0:1]
	s_mov_b32 m0, s40
	v_lshl_add_u64 v[216:217], s[18:19], 0, v[132:133]
	global_load_lds_dwordx4 v[214:215], off
	v_lshl_add_u64 v[214:215], s[38:39], 0, v[130:131]
	s_add_i32 m0, s40, 0x2000
	s_nop 0
	global_load_lds_dwordx4 v[214:215], off
	v_lshl_add_u64 v[214:215], s[18:19], 0, v[134:135]
	s_mov_b32 m0, s23
	s_nop 0
	global_load_lds_dwordx4 v[214:215], off
	s_mov_b32 m0, s24
	s_nop 0
	global_load_lds_dwordx4 v[216:217], off
	s_waitcnt vmcnt(8)
	s_waitcnt lgkmcnt(0)
	s_barrier
	s_waitcnt lgkmcnt(0)
	v_mfma_f32_16x16x32_bf16 v[62:65], v[142:145], v[178:181], 0
	v_mfma_f32_16x16x32_bf16 v[62:65], v[146:149], v[182:185], v[62:65]
	v_mfma_f32_16x16x32_bf16 v[58:61], v[162:165], v[178:181], 0
	v_mfma_f32_16x16x32_bf16 v[58:61], v[166:169], v[182:185], v[58:61]
	v_mfma_f32_16x16x32_bf16 v[54:57], v[150:153], v[178:181], 0
	v_mfma_f32_16x16x32_bf16 v[54:57], v[154:157], v[182:185], v[54:57]
	v_mfma_f32_16x16x32_bf16 v[50:53], v[170:173], v[178:181], 0
	v_mfma_f32_16x16x32_bf16 v[50:53], v[174:177], v[182:185], v[50:53]
	v_mfma_f32_16x16x32_bf16 v[46:49], v[142:145], v[186:189], 0
	v_mfma_f32_16x16x32_bf16 v[46:49], v[146:149], v[190:193], v[46:49]
	v_mfma_f32_16x16x32_bf16 v[42:45], v[162:165], v[186:189], 0
	v_mfma_f32_16x16x32_bf16 v[42:45], v[166:169], v[190:193], v[42:45]
	v_mfma_f32_16x16x32_bf16 v[38:41], v[150:153], v[186:189], 0
	v_mfma_f32_16x16x32_bf16 v[38:41], v[154:157], v[190:193], v[38:41]
	v_mfma_f32_16x16x32_bf16 v[34:37], v[170:173], v[186:189], 0
	v_mfma_f32_16x16x32_bf16 v[34:37], v[174:177], v[190:193], v[34:37]
	v_mfma_f32_16x16x32_bf16 v[30:33], v[142:145], v[194:197], 0
	v_mfma_f32_16x16x32_bf16 v[30:33], v[146:149], v[198:201], v[30:33]
	v_mfma_f32_16x16x32_bf16 v[26:29], v[162:165], v[194:197], 0
	v_mfma_f32_16x16x32_bf16 v[26:29], v[166:169], v[198:201], v[26:29]
	v_mfma_f32_16x16x32_bf16 v[22:25], v[150:153], v[194:197], 0
	v_mfma_f32_16x16x32_bf16 v[22:25], v[154:157], v[198:201], v[22:25]
	v_mfma_f32_16x16x32_bf16 v[18:21], v[170:173], v[194:197], 0
	v_mfma_f32_16x16x32_bf16 v[18:21], v[174:177], v[198:201], v[18:21]
	v_mfma_f32_16x16x32_bf16 v[14:17], v[142:145], v[202:205], 0
	v_mfma_f32_16x16x32_bf16 v[14:17], v[146:149], v[206:209], v[14:17]
	v_mfma_f32_16x16x32_bf16 v[10:13], v[162:165], v[202:205], 0
	v_mfma_f32_16x16x32_bf16 v[10:13], v[166:169], v[206:209], v[10:13]
	v_mfma_f32_16x16x32_bf16 v[6:9], v[150:153], v[202:205], 0
	v_mfma_f32_16x16x32_bf16 v[6:9], v[154:157], v[206:209], v[6:9]
	v_mfma_f32_16x16x32_bf16 v[2:5], v[170:173], v[202:205], 0
	v_mfma_f32_16x16x32_bf16 v[2:5], v[174:177], v[206:209], v[2:5]
	s_barrier
	s_add_i32 s38, 0, 0x18000
	s_add_i32 s39, 0, 0x1c000
	v_add_u32_e32 v154, s38, v159
	v_add_u32_e32 v174, s39, v159
	ds_read_b128 v[142:145], v154
	ds_read_b128 v[146:149], v154 offset:1024
	ds_read_b128 v[150:153], v154 offset:2048
	ds_read_b128 v[154:157], v154 offset:3072
	ds_read_b128 v[162:165], v174
	ds_read_b128 v[166:169], v174 offset:1024
	ds_read_b128 v[170:173], v174 offset:2048
	ds_read_b128 v[174:177], v174 offset:3072
	s_add_u32 s18, s18, 0x40000
	s_addc_u32 s19, s19, 0
	s_mov_b32 m0, s25
	v_lshl_add_u64 v[218:219], s[18:19], 0, v[134:135]
	ds_read_b128 v[178:181], v161 offset:32768
	ds_read_b128 v[182:185], v161 offset:33792
	ds_read_b128 v[186:189], v161 offset:34816
	ds_read_b128 v[190:193], v161 offset:35840
	ds_read_b128 v[194:197], v161 offset:36864
	ds_read_b128 v[198:201], v161 offset:37888
	ds_read_b128 v[202:205], v161 offset:38912
	ds_read_b128 v[206:209], v161 offset:39936
	global_load_lds_dwordx4 v[218:219], off
	v_lshl_add_u64 v[218:219], s[18:19], 0, v[132:133]
	s_mov_b32 m0, s26
	s_nop 0
	global_load_lds_dwordx4 v[218:219], off
	s_waitcnt vmcnt(8)
	s_waitcnt lgkmcnt(0)
	s_barrier
	s_waitcnt lgkmcnt(0)
	v_mfma_f32_16x16x32_bf16 v[126:129], v[142:145], v[178:181], v[126:129]
	v_mfma_f32_16x16x32_bf16 v[126:129], v[146:149], v[182:185], v[126:129]
	v_mfma_f32_16x16x32_bf16 v[122:125], v[162:165], v[178:181], v[122:125]
	v_mfma_f32_16x16x32_bf16 v[122:125], v[166:169], v[182:185], v[122:125]
	v_mfma_f32_16x16x32_bf16 v[118:121], v[150:153], v[178:181], v[118:121]
	v_mfma_f32_16x16x32_bf16 v[118:121], v[154:157], v[182:185], v[118:121]
	v_mfma_f32_16x16x32_bf16 v[114:117], v[170:173], v[178:181], v[114:117]
	v_mfma_f32_16x16x32_bf16 v[114:117], v[174:177], v[182:185], v[114:117]
	v_mfma_f32_16x16x32_bf16 v[110:113], v[142:145], v[186:189], v[110:113]
	v_mfma_f32_16x16x32_bf16 v[110:113], v[146:149], v[190:193], v[110:113]
	v_mfma_f32_16x16x32_bf16 v[106:109], v[162:165], v[186:189], v[106:109]
	v_mfma_f32_16x16x32_bf16 v[106:109], v[166:169], v[190:193], v[106:109]
	v_mfma_f32_16x16x32_bf16 v[102:105], v[150:153], v[186:189], v[102:105]
	v_mfma_f32_16x16x32_bf16 v[102:105], v[154:157], v[190:193], v[102:105]
	v_mfma_f32_16x16x32_bf16 v[98:101], v[170:173], v[186:189], v[98:101]
	v_mfma_f32_16x16x32_bf16 v[98:101], v[174:177], v[190:193], v[98:101]
	v_mfma_f32_16x16x32_bf16 v[94:97], v[142:145], v[194:197], v[94:97]
	v_mfma_f32_16x16x32_bf16 v[94:97], v[146:149], v[198:201], v[94:97]
	v_mfma_f32_16x16x32_bf16 v[90:93], v[162:165], v[194:197], v[90:93]
	v_mfma_f32_16x16x32_bf16 v[90:93], v[166:169], v[198:201], v[90:93]
	v_mfma_f32_16x16x32_bf16 v[86:89], v[150:153], v[194:197], v[86:89]
	v_mfma_f32_16x16x32_bf16 v[86:89], v[154:157], v[198:201], v[86:89]
	v_mfma_f32_16x16x32_bf16 v[82:85], v[170:173], v[194:197], v[82:85]
	v_mfma_f32_16x16x32_bf16 v[82:85], v[174:177], v[198:201], v[82:85]
	v_mfma_f32_16x16x32_bf16 v[78:81], v[142:145], v[202:205], v[78:81]
	v_mfma_f32_16x16x32_bf16 v[78:81], v[146:149], v[206:209], v[78:81]
	v_mfma_f32_16x16x32_bf16 v[74:77], v[162:165], v[202:205], v[74:77]
	v_mfma_f32_16x16x32_bf16 v[74:77], v[166:169], v[206:209], v[74:77]
	v_mfma_f32_16x16x32_bf16 v[70:73], v[150:153], v[202:205], v[70:73]
	v_mfma_f32_16x16x32_bf16 v[70:73], v[154:157], v[206:209], v[70:73]
	v_mfma_f32_16x16x32_bf16 v[66:69], v[170:173], v[202:205], v[66:69]
	v_mfma_f32_16x16x32_bf16 v[66:69], v[174:177], v[206:209], v[66:69]
	s_barrier
	s_add_i32 s18, s38, s22
	v_lshl_add_u64 v[210:211], v[210:211], 0, s[74:75]
	s_mov_b32 m0, s18
	ds_read_b128 v[178:181], v161 offset:49152
	ds_read_b128 v[182:185], v161 offset:50176
	ds_read_b128 v[186:189], v161 offset:51200
	ds_read_b128 v[190:193], v161 offset:52224
	ds_read_b128 v[194:197], v161 offset:53248
	ds_read_b128 v[198:201], v161 offset:54272
	ds_read_b128 v[202:205], v161 offset:55296
	ds_read_b128 v[206:209], v161 offset:56320
	global_load_lds_dwordx4 v[210:211], off
	s_add_i32 m0, s18, 0x2000
	s_add_u32 s2, s2, 0x40080
	v_lshl_add_u64 v[210:211], v[212:213], 0, s[74:75]
	s_addc_u32 s3, s3, 0
	s_add_i32 s18, s39, s22
	global_load_lds_dwordx4 v[210:211], off
	v_lshl_add_u64 v[210:211], s[2:3], 0, v[0:1]
	s_mov_b32 m0, s18
	s_nop 0
	global_load_lds_dwordx4 v[210:211], off
	v_lshl_add_u64 v[210:211], s[2:3], 0, v[130:131]
	s_add_i32 m0, s18, 0x2000
	s_nop 0
	global_load_lds_dwordx4 v[210:211], off
	v_lshl_add_u64 v[210:211], v[214:215], 0, s[74:75]
	s_mov_b32 m0, s27
	s_nop 0
	global_load_lds_dwordx4 v[210:211], off
	v_lshl_add_u64 v[210:211], v[216:217], 0, s[74:75]
	s_mov_b32 m0, s28
	s_nop 0
	global_load_lds_dwordx4 v[210:211], off
	s_waitcnt vmcnt(8)
	s_waitcnt lgkmcnt(0)
	s_barrier
	s_waitcnt lgkmcnt(0)
	v_mfma_f32_16x16x32_bf16 v[62:65], v[142:145], v[178:181], v[62:65]
	v_mfma_f32_16x16x32_bf16 v[62:65], v[146:149], v[182:185], v[62:65]
	v_mfma_f32_16x16x32_bf16 v[58:61], v[162:165], v[178:181], v[58:61]
	v_mfma_f32_16x16x32_bf16 v[58:61], v[166:169], v[182:185], v[58:61]
	v_mfma_f32_16x16x32_bf16 v[54:57], v[150:153], v[178:181], v[54:57]
	v_mfma_f32_16x16x32_bf16 v[54:57], v[154:157], v[182:185], v[54:57]
	v_mfma_f32_16x16x32_bf16 v[50:53], v[170:173], v[178:181], v[50:53]
	v_mfma_f32_16x16x32_bf16 v[50:53], v[174:177], v[182:185], v[50:53]
	v_mfma_f32_16x16x32_bf16 v[46:49], v[142:145], v[186:189], v[46:49]
	v_mfma_f32_16x16x32_bf16 v[46:49], v[146:149], v[190:193], v[46:49]
	v_mfma_f32_16x16x32_bf16 v[42:45], v[162:165], v[186:189], v[42:45]
	v_mfma_f32_16x16x32_bf16 v[42:45], v[166:169], v[190:193], v[42:45]
	v_mfma_f32_16x16x32_bf16 v[38:41], v[150:153], v[186:189], v[38:41]
	v_mfma_f32_16x16x32_bf16 v[38:41], v[154:157], v[190:193], v[38:41]
	v_mfma_f32_16x16x32_bf16 v[34:37], v[170:173], v[186:189], v[34:37]
	v_mfma_f32_16x16x32_bf16 v[34:37], v[174:177], v[190:193], v[34:37]
	v_mfma_f32_16x16x32_bf16 v[30:33], v[142:145], v[194:197], v[30:33]
	v_mfma_f32_16x16x32_bf16 v[30:33], v[146:149], v[198:201], v[30:33]
	v_mfma_f32_16x16x32_bf16 v[26:29], v[162:165], v[194:197], v[26:29]
	v_mfma_f32_16x16x32_bf16 v[26:29], v[166:169], v[198:201], v[26:29]
	v_mfma_f32_16x16x32_bf16 v[22:25], v[150:153], v[194:197], v[22:25]
	v_mfma_f32_16x16x32_bf16 v[22:25], v[154:157], v[198:201], v[22:25]
	v_mfma_f32_16x16x32_bf16 v[18:21], v[170:173], v[194:197], v[18:21]
	v_mfma_f32_16x16x32_bf16 v[18:21], v[174:177], v[198:201], v[18:21]
	v_mfma_f32_16x16x32_bf16 v[14:17], v[142:145], v[202:205], v[14:17]
	v_mfma_f32_16x16x32_bf16 v[14:17], v[146:149], v[206:209], v[14:17]
	v_mfma_f32_16x16x32_bf16 v[10:13], v[162:165], v[202:205], v[10:13]
	v_mfma_f32_16x16x32_bf16 v[10:13], v[166:169], v[206:209], v[10:13]
	v_mfma_f32_16x16x32_bf16 v[6:9], v[150:153], v[202:205], v[6:9]
	v_mfma_f32_16x16x32_bf16 v[6:9], v[154:157], v[206:209], v[6:9]
	v_mfma_f32_16x16x32_bf16 v[2:5], v[170:173], v[202:205], v[2:5]
	v_mfma_f32_16x16x32_bf16 v[2:5], v[174:177], v[206:209], v[2:5]
	s_barrier
	s_add_i32 s37, s37, 2
	s_add_u32 s16, s16, 0x100
	s_addc_u32 s17, s17, 0
	s_add_u32 s33, s33, 0x100
	s_addc_u32 s36, s36, 0
	s_cmp_gt_u32 s37, 13
.LBB0_598:
	s_add_u32 s2, s16, 0xfffc0080
	s_addc_u32 s3, s17, -1
	s_add_i32 s38, 0, 0x10000
	s_cmp_eq_u32 s37, 12
	s_cselect_b32 s19, s9, s3
	s_cselect_b32 s18, s34, s2
	s_cselect_b32 s3, s11, s36
	s_cselect_b32 s2, s35, s33
	s_add_i32 s40, 0, 0x14000
	v_add_u32_e32 v154, s38, v159
	v_add_u32_e32 v174, s40, v159
	ds_read_b128 v[142:145], v154
	ds_read_b128 v[146:149], v154 offset:1024
	ds_read_b128 v[150:153], v154 offset:2048
	ds_read_b128 v[154:157], v154 offset:3072
	ds_read_b128 v[162:165], v174
	ds_read_b128 v[166:169], v174 offset:1024
	ds_read_b128 v[170:173], v174 offset:2048
	ds_read_b128 v[174:177], v174 offset:3072
	v_lshl_add_u64 v[210:211], s[16:17], 0, v[138:139]
	s_add_i32 m0, s23, 0xc000
	ds_read_b128 v[178:181], v161
	ds_read_b128 v[182:185], v161 offset:1024
	ds_read_b128 v[186:189], v161 offset:2048
	ds_read_b128 v[190:193], v161 offset:3072
	ds_read_b128 v[194:197], v161 offset:4096
	ds_read_b128 v[198:201], v161 offset:5120
	ds_read_b128 v[202:205], v161 offset:6144
	ds_read_b128 v[206:209], v161 offset:7168
	global_load_lds_dwordx4 v[210:211], off
	v_lshl_add_u64 v[210:211], s[16:17], 0, v[140:141]
	s_add_i32 m0, s23, 0xe000
	s_nop 0
	global_load_lds_dwordx4 v[210:211], off
	s_waitcnt vmcnt(8)
	s_waitcnt lgkmcnt(0)
	s_barrier
	s_waitcnt lgkmcnt(0)
	v_mfma_f32_16x16x32_bf16 v[126:129], v[142:145], v[178:181], v[126:129]
	v_mfma_f32_16x16x32_bf16 v[126:129], v[146:149], v[182:185], v[126:129]
	v_mfma_f32_16x16x32_bf16 v[122:125], v[162:165], v[178:181], v[122:125]
	v_mfma_f32_16x16x32_bf16 v[122:125], v[166:169], v[182:185], v[122:125]
	v_mfma_f32_16x16x32_bf16 v[118:121], v[150:153], v[178:181], v[118:121]
	v_mfma_f32_16x16x32_bf16 v[118:121], v[154:157], v[182:185], v[118:121]
	v_mfma_f32_16x16x32_bf16 v[114:117], v[170:173], v[178:181], v[114:117]
	v_mfma_f32_16x16x32_bf16 v[114:117], v[174:177], v[182:185], v[114:117]
	v_mfma_f32_16x16x32_bf16 v[110:113], v[142:145], v[186:189], v[110:113]
	v_mfma_f32_16x16x32_bf16 v[110:113], v[146:149], v[190:193], v[110:113]
	v_mfma_f32_16x16x32_bf16 v[106:109], v[162:165], v[186:189], v[106:109]
	v_mfma_f32_16x16x32_bf16 v[106:109], v[166:169], v[190:193], v[106:109]
	v_mfma_f32_16x16x32_bf16 v[102:105], v[150:153], v[186:189], v[102:105]
	v_mfma_f32_16x16x32_bf16 v[102:105], v[154:157], v[190:193], v[102:105]
	v_mfma_f32_16x16x32_bf16 v[98:101], v[170:173], v[186:189], v[98:101]
	v_mfma_f32_16x16x32_bf16 v[98:101], v[174:177], v[190:193], v[98:101]
	v_mfma_f32_16x16x32_bf16 v[94:97], v[142:145], v[194:197], v[94:97]
	v_mfma_f32_16x16x32_bf16 v[94:97], v[146:149], v[198:201], v[94:97]
	v_mfma_f32_16x16x32_bf16 v[90:93], v[162:165], v[194:197], v[90:93]
	v_mfma_f32_16x16x32_bf16 v[90:93], v[166:169], v[198:201], v[90:93]
	v_mfma_f32_16x16x32_bf16 v[86:89], v[150:153], v[194:197], v[86:89]
	v_mfma_f32_16x16x32_bf16 v[86:89], v[154:157], v[198:201], v[86:89]
	v_mfma_f32_16x16x32_bf16 v[82:85], v[170:173], v[194:197], v[82:85]
	v_mfma_f32_16x16x32_bf16 v[82:85], v[174:177], v[198:201], v[82:85]
	v_mfma_f32_16x16x32_bf16 v[78:81], v[142:145], v[202:205], v[78:81]
	v_mfma_f32_16x16x32_bf16 v[78:81], v[146:149], v[206:209], v[78:81]
	v_mfma_f32_16x16x32_bf16 v[74:77], v[162:165], v[202:205], v[74:77]
	v_mfma_f32_16x16x32_bf16 v[74:77], v[166:169], v[206:209], v[74:77]
	v_mfma_f32_16x16x32_bf16 v[70:73], v[150:153], v[202:205], v[70:73]
	v_mfma_f32_16x16x32_bf16 v[70:73], v[154:157], v[206:209], v[70:73]
	v_mfma_f32_16x16x32_bf16 v[66:69], v[170:173], v[202:205], v[66:69]
	v_mfma_f32_16x16x32_bf16 v[66:69], v[174:177], v[206:209], v[66:69]
	s_barrier
	s_add_i32 s38, s38, s22
	v_lshl_add_u64 v[210:211], s[2:3], 0, v[0:1]
	s_mov_b32 m0, s38
	ds_read_b128 v[178:181], v161 offset:16384
	ds_read_b128 v[182:185], v161 offset:17408
	ds_read_b128 v[186:189], v161 offset:18432
	ds_read_b128 v[190:193], v161 offset:19456
	ds_read_b128 v[194:197], v161 offset:20480
	ds_read_b128 v[198:201], v161 offset:21504
	ds_read_b128 v[202:205], v161 offset:22528
	ds_read_b128 v[206:209], v161 offset:23552
	global_load_lds_dwordx4 v[210:211], off
	s_add_i32 m0, s38, 0x2000
	s_add_u32 s38, s2, 0x40000
	v_lshl_add_u64 v[212:213], s[2:3], 0, v[130:131]
	s_addc_u32 s39, s3, 0
	s_add_i32 s40, s40, s22
	global_load_lds_dwordx4 v[212:213], off
	v_lshl_add_u64 v[214:215], s[38:39], 0, v[0:1]
	s_mov_b32 m0, s40
	v_lshl_add_u64 v[216:217], s[18:19], 0, v[132:133]
	global_load_lds_dwordx4 v[214:215], off
	v_lshl_add_u64 v[214:215], s[38:39], 0, v[130:131]
	s_add_i32 m0, s40, 0x2000
	s_nop 0
	global_load_lds_dwordx4 v[214:215], off
	v_lshl_add_u64 v[214:215], s[18:19], 0, v[134:135]
	s_mov_b32 m0, s23
	s_nop 0
	global_load_lds_dwordx4 v[214:215], off
	s_mov_b32 m0, s24
	s_nop 0
	global_load_lds_dwordx4 v[216:217], off
	s_waitcnt vmcnt(8)
	s_waitcnt lgkmcnt(0)
	s_barrier
	s_waitcnt lgkmcnt(0)
	v_mfma_f32_16x16x32_bf16 v[62:65], v[142:145], v[178:181], v[62:65]
	v_mfma_f32_16x16x32_bf16 v[62:65], v[146:149], v[182:185], v[62:65]
	v_mfma_f32_16x16x32_bf16 v[58:61], v[162:165], v[178:181], v[58:61]
	v_mfma_f32_16x16x32_bf16 v[58:61], v[166:169], v[182:185], v[58:61]
	v_mfma_f32_16x16x32_bf16 v[54:57], v[150:153], v[178:181], v[54:57]
	v_mfma_f32_16x16x32_bf16 v[54:57], v[154:157], v[182:185], v[54:57]
	v_mfma_f32_16x16x32_bf16 v[50:53], v[170:173], v[178:181], v[50:53]
	v_mfma_f32_16x16x32_bf16 v[50:53], v[174:177], v[182:185], v[50:53]
	v_mfma_f32_16x16x32_bf16 v[46:49], v[142:145], v[186:189], v[46:49]
	v_mfma_f32_16x16x32_bf16 v[46:49], v[146:149], v[190:193], v[46:49]
	v_mfma_f32_16x16x32_bf16 v[42:45], v[162:165], v[186:189], v[42:45]
	v_mfma_f32_16x16x32_bf16 v[42:45], v[166:169], v[190:193], v[42:45]
	v_mfma_f32_16x16x32_bf16 v[38:41], v[150:153], v[186:189], v[38:41]
	v_mfma_f32_16x16x32_bf16 v[38:41], v[154:157], v[190:193], v[38:41]
	v_mfma_f32_16x16x32_bf16 v[34:37], v[170:173], v[186:189], v[34:37]
	v_mfma_f32_16x16x32_bf16 v[34:37], v[174:177], v[190:193], v[34:37]
	v_mfma_f32_16x16x32_bf16 v[30:33], v[142:145], v[194:197], v[30:33]
	v_mfma_f32_16x16x32_bf16 v[30:33], v[146:149], v[198:201], v[30:33]
	v_mfma_f32_16x16x32_bf16 v[26:29], v[162:165], v[194:197], v[26:29]
	v_mfma_f32_16x16x32_bf16 v[26:29], v[166:169], v[198:201], v[26:29]
	v_mfma_f32_16x16x32_bf16 v[22:25], v[150:153], v[194:197], v[22:25]
	v_mfma_f32_16x16x32_bf16 v[22:25], v[154:157], v[198:201], v[22:25]
	v_mfma_f32_16x16x32_bf16 v[18:21], v[170:173], v[194:197], v[18:21]
	v_mfma_f32_16x16x32_bf16 v[18:21], v[174:177], v[198:201], v[18:21]
	v_mfma_f32_16x16x32_bf16 v[14:17], v[142:145], v[202:205], v[14:17]
	v_mfma_f32_16x16x32_bf16 v[14:17], v[146:149], v[206:209], v[14:17]
	v_mfma_f32_16x16x32_bf16 v[10:13], v[162:165], v[202:205], v[10:13]
	v_mfma_f32_16x16x32_bf16 v[10:13], v[166:169], v[206:209], v[10:13]
	v_mfma_f32_16x16x32_bf16 v[6:9], v[150:153], v[202:205], v[6:9]
	v_mfma_f32_16x16x32_bf16 v[6:9], v[154:157], v[206:209], v[6:9]
	v_mfma_f32_16x16x32_bf16 v[2:5], v[170:173], v[202:205], v[2:5]
	v_mfma_f32_16x16x32_bf16 v[2:5], v[174:177], v[206:209], v[2:5]
	s_barrier
	s_add_i32 s38, 0, 0x18000
	s_add_i32 s39, 0, 0x1c000
	v_add_u32_e32 v154, s38, v159
	v_add_u32_e32 v174, s39, v159
	ds_read_b128 v[142:145], v154
	ds_read_b128 v[146:149], v154 offset:1024
	ds_read_b128 v[150:153], v154 offset:2048
	ds_read_b128 v[154:157], v154 offset:3072
	ds_read_b128 v[162:165], v174
	ds_read_b128 v[166:169], v174 offset:1024
	ds_read_b128 v[170:173], v174 offset:2048
	ds_read_b128 v[174:177], v174 offset:3072
	s_add_u32 s18, s18, 0x40000
	s_addc_u32 s19, s19, 0
	s_mov_b32 m0, s25
	v_lshl_add_u64 v[218:219], s[18:19], 0, v[134:135]
	ds_read_b128 v[178:181], v161 offset:32768
	ds_read_b128 v[182:185], v161 offset:33792
	ds_read_b128 v[186:189], v161 offset:34816
	ds_read_b128 v[190:193], v161 offset:35840
	ds_read_b128 v[194:197], v161 offset:36864
	ds_read_b128 v[198:201], v161 offset:37888
	ds_read_b128 v[202:205], v161 offset:38912
	ds_read_b128 v[206:209], v161 offset:39936
	global_load_lds_dwordx4 v[218:219], off
	v_lshl_add_u64 v[218:219], s[18:19], 0, v[132:133]
	s_mov_b32 m0, s26
	s_nop 0
	global_load_lds_dwordx4 v[218:219], off
	s_waitcnt vmcnt(8)
	s_waitcnt lgkmcnt(0)
	s_barrier
	s_waitcnt lgkmcnt(0)
	v_mfma_f32_16x16x32_bf16 v[126:129], v[142:145], v[178:181], v[126:129]
	v_mfma_f32_16x16x32_bf16 v[126:129], v[146:149], v[182:185], v[126:129]
	v_mfma_f32_16x16x32_bf16 v[122:125], v[162:165], v[178:181], v[122:125]
	v_mfma_f32_16x16x32_bf16 v[122:125], v[166:169], v[182:185], v[122:125]
	v_mfma_f32_16x16x32_bf16 v[118:121], v[150:153], v[178:181], v[118:121]
	v_mfma_f32_16x16x32_bf16 v[118:121], v[154:157], v[182:185], v[118:121]
	v_mfma_f32_16x16x32_bf16 v[114:117], v[170:173], v[178:181], v[114:117]
	v_mfma_f32_16x16x32_bf16 v[114:117], v[174:177], v[182:185], v[114:117]
	v_mfma_f32_16x16x32_bf16 v[110:113], v[142:145], v[186:189], v[110:113]
	v_mfma_f32_16x16x32_bf16 v[110:113], v[146:149], v[190:193], v[110:113]
	v_mfma_f32_16x16x32_bf16 v[106:109], v[162:165], v[186:189], v[106:109]
	v_mfma_f32_16x16x32_bf16 v[106:109], v[166:169], v[190:193], v[106:109]
	v_mfma_f32_16x16x32_bf16 v[102:105], v[150:153], v[186:189], v[102:105]
	v_mfma_f32_16x16x32_bf16 v[102:105], v[154:157], v[190:193], v[102:105]
	v_mfma_f32_16x16x32_bf16 v[98:101], v[170:173], v[186:189], v[98:101]
	v_mfma_f32_16x16x32_bf16 v[98:101], v[174:177], v[190:193], v[98:101]
	v_mfma_f32_16x16x32_bf16 v[94:97], v[142:145], v[194:197], v[94:97]
	v_mfma_f32_16x16x32_bf16 v[94:97], v[146:149], v[198:201], v[94:97]
	v_mfma_f32_16x16x32_bf16 v[90:93], v[162:165], v[194:197], v[90:93]
	v_mfma_f32_16x16x32_bf16 v[90:93], v[166:169], v[198:201], v[90:93]
	v_mfma_f32_16x16x32_bf16 v[86:89], v[150:153], v[194:197], v[86:89]
	v_mfma_f32_16x16x32_bf16 v[86:89], v[154:157], v[198:201], v[86:89]
	v_mfma_f32_16x16x32_bf16 v[82:85], v[170:173], v[194:197], v[82:85]
	v_mfma_f32_16x16x32_bf16 v[82:85], v[174:177], v[198:201], v[82:85]
	v_mfma_f32_16x16x32_bf16 v[78:81], v[142:145], v[202:205], v[78:81]
	v_mfma_f32_16x16x32_bf16 v[78:81], v[146:149], v[206:209], v[78:81]
	v_mfma_f32_16x16x32_bf16 v[74:77], v[162:165], v[202:205], v[74:77]
	v_mfma_f32_16x16x32_bf16 v[74:77], v[166:169], v[206:209], v[74:77]
	v_mfma_f32_16x16x32_bf16 v[70:73], v[150:153], v[202:205], v[70:73]
	v_mfma_f32_16x16x32_bf16 v[70:73], v[154:157], v[206:209], v[70:73]
	v_mfma_f32_16x16x32_bf16 v[66:69], v[170:173], v[202:205], v[66:69]
	v_mfma_f32_16x16x32_bf16 v[66:69], v[174:177], v[206:209], v[66:69]
	s_barrier
	s_add_i32 s18, s38, s22
	v_lshl_add_u64 v[210:211], v[210:211], 0, s[74:75]
	s_mov_b32 m0, s18
	ds_read_b128 v[178:181], v161 offset:49152
	ds_read_b128 v[182:185], v161 offset:50176
	ds_read_b128 v[186:189], v161 offset:51200
	ds_read_b128 v[190:193], v161 offset:52224
	ds_read_b128 v[194:197], v161 offset:53248
	ds_read_b128 v[198:201], v161 offset:54272
	ds_read_b128 v[202:205], v161 offset:55296
	ds_read_b128 v[206:209], v161 offset:56320
	global_load_lds_dwordx4 v[210:211], off
	s_add_i32 m0, s18, 0x2000
	s_add_u32 s2, s2, 0x40080
	v_lshl_add_u64 v[210:211], v[212:213], 0, s[74:75]
	s_addc_u32 s3, s3, 0
	s_add_i32 s18, s39, s22
	global_load_lds_dwordx4 v[210:211], off
	v_lshl_add_u64 v[210:211], s[2:3], 0, v[0:1]
	s_mov_b32 m0, s18
	s_nop 0
	global_load_lds_dwordx4 v[210:211], off
	v_lshl_add_u64 v[210:211], s[2:3], 0, v[130:131]
	s_add_i32 m0, s18, 0x2000
	s_nop 0
	global_load_lds_dwordx4 v[210:211], off
	v_lshl_add_u64 v[210:211], v[214:215], 0, s[74:75]
	s_mov_b32 m0, s27
	s_nop 0
	global_load_lds_dwordx4 v[210:211], off
	v_lshl_add_u64 v[210:211], v[216:217], 0, s[74:75]
	s_mov_b32 m0, s28
	s_nop 0
	global_load_lds_dwordx4 v[210:211], off
	s_waitcnt vmcnt(8)
	s_waitcnt lgkmcnt(0)
	s_barrier
	s_waitcnt lgkmcnt(0)
	v_mfma_f32_16x16x32_bf16 v[62:65], v[142:145], v[178:181], v[62:65]
	v_mfma_f32_16x16x32_bf16 v[62:65], v[146:149], v[182:185], v[62:65]
	v_mfma_f32_16x16x32_bf16 v[58:61], v[162:165], v[178:181], v[58:61]
	v_mfma_f32_16x16x32_bf16 v[58:61], v[166:169], v[182:185], v[58:61]
	v_mfma_f32_16x16x32_bf16 v[54:57], v[150:153], v[178:181], v[54:57]
	v_mfma_f32_16x16x32_bf16 v[54:57], v[154:157], v[182:185], v[54:57]
	v_mfma_f32_16x16x32_bf16 v[50:53], v[170:173], v[178:181], v[50:53]
	v_mfma_f32_16x16x32_bf16 v[50:53], v[174:177], v[182:185], v[50:53]
	v_mfma_f32_16x16x32_bf16 v[46:49], v[142:145], v[186:189], v[46:49]
	v_mfma_f32_16x16x32_bf16 v[46:49], v[146:149], v[190:193], v[46:49]
	v_mfma_f32_16x16x32_bf16 v[42:45], v[162:165], v[186:189], v[42:45]
	v_mfma_f32_16x16x32_bf16 v[42:45], v[166:169], v[190:193], v[42:45]
	v_mfma_f32_16x16x32_bf16 v[38:41], v[150:153], v[186:189], v[38:41]
	v_mfma_f32_16x16x32_bf16 v[38:41], v[154:157], v[190:193], v[38:41]
	v_mfma_f32_16x16x32_bf16 v[34:37], v[170:173], v[186:189], v[34:37]
	v_mfma_f32_16x16x32_bf16 v[34:37], v[174:177], v[190:193], v[34:37]
	v_mfma_f32_16x16x32_bf16 v[30:33], v[142:145], v[194:197], v[30:33]
	v_mfma_f32_16x16x32_bf16 v[30:33], v[146:149], v[198:201], v[30:33]
	v_mfma_f32_16x16x32_bf16 v[26:29], v[162:165], v[194:197], v[26:29]
	v_mfma_f32_16x16x32_bf16 v[26:29], v[166:169], v[198:201], v[26:29]
	v_mfma_f32_16x16x32_bf16 v[22:25], v[150:153], v[194:197], v[22:25]
	v_mfma_f32_16x16x32_bf16 v[22:25], v[154:157], v[198:201], v[22:25]
	v_mfma_f32_16x16x32_bf16 v[18:21], v[170:173], v[194:197], v[18:21]
	v_mfma_f32_16x16x32_bf16 v[18:21], v[174:177], v[198:201], v[18:21]
	v_mfma_f32_16x16x32_bf16 v[14:17], v[142:145], v[202:205], v[14:17]
	v_mfma_f32_16x16x32_bf16 v[14:17], v[146:149], v[206:209], v[14:17]
	v_mfma_f32_16x16x32_bf16 v[10:13], v[162:165], v[202:205], v[10:13]
	v_mfma_f32_16x16x32_bf16 v[10:13], v[166:169], v[206:209], v[10:13]
	v_mfma_f32_16x16x32_bf16 v[6:9], v[150:153], v[202:205], v[6:9]
	v_mfma_f32_16x16x32_bf16 v[6:9], v[154:157], v[206:209], v[6:9]
	v_mfma_f32_16x16x32_bf16 v[2:5], v[170:173], v[202:205], v[2:5]
	v_mfma_f32_16x16x32_bf16 v[2:5], v[174:177], v[206:209], v[2:5]
	s_barrier
	s_add_i32 s37, s37, 2
	s_add_u32 s16, s16, 0x100
	s_addc_u32 s17, s17, 0
	s_add_u32 s33, s33, 0x100
	s_addc_u32 s36, s36, 0
	s_cmp_gt_u32 s37, 13
	s_cbranch_scc0 .LBB0_598
	s_and_b64 vcc, exec, s[6:7]
	s_cbranch_vccz .LBB0_601
	s_barrier
